# v13 + GEMM K-loops: next-stage LDS-DMA issue staggered between the two waves of a SIMD (waves 4-7 issue after two MFMA groups of the next step)
# speedup vs baseline: 1.0233x; 1.0047x over previous
;   DI unsigned rowoff(int m) const { int combo = m >> 9, n = m & 511, b = combo >> 1, g = combo & 1; return (unsigned)((b * SEQ + 16 * n) * EIN + col0 + g * 64); }
;   DI unsigned koff(int k) const { return (unsigned)((k >> 6) * EIN + (k & 63)); }
; DI void dma16(const void* g, unsigned char* l) { __builtin_amdgcn_global_load_lds((const unsigned*)g, (lds_u32_t*)(unsigned)(size_t)l, 16, 0, 0); }
; template <class AF, class EF>
; DI void gemm_run(unsigned char* lds, int wv, const AF& af, const bf16_t* __restrict__ Bt, int ldb, int M, int N, int K, const EF& ef, int blk_off) {
;     ...
;   for (int tile_ = first; tile_ < ntl_eff; tile_ += tstep) {
;     int nt, mt;
;     if (xmap) { nt = tile_ % ntiles; mt = (tile_ / ntiles) * 8 + ((int)blockIdx.x & 7); }
;     else { nt = tile_ % ntiles; mt = tile_ / ntiles; }
;     const int m0 = mt << 8, n0 = nt << 8;
;     f32x4 acc[4][8];
; #pragma unroll
;     for (int i = 0; i < 4; ++i)
; #pragma unroll
;       for (int j = 0; j < 8; ++j) acc[i][j] = (f32x4){0.f, 0.f, 0.f, 0.f};
;     unsigned aoff[4], boff[4];
;     const bf16_t* Ab = af.base();
; #pragma unroll
;     for (int i = 0; i < 4; ++i) {
;       int row = crow + 64 * i;
;       aoff[i] = af.rowoff(m0 + row);
;       int n = n0 + row; n = n < N ? n : N - 1;
;       boff[i] = (unsigned)(n * ldb + cch);
;     }
;     __syncthreads();
; #pragma unroll
;     for (int i = 0; i < 4; ++i) {
;       dma16(Ab + aoff[i] + af.koff(cch), sBase + 32768 + (i * 512 + tid) * 16);
;       dma16(Bt + boff[i], sBase + (i * 512 + tid) * 16);
;     }
.LBB0_119:
	s_mul_hi_i32 s4, s2, 0x2aaaaaab
	s_lshr_b32 s5, s4, 31
	s_ashr_i32 s4, s4, 1
	s_add_i32 s7, s4, s5
	s_lshl_b32 s4, s7, 3
	s_or_b32 s6, s4, s78
	v_readlane_b32 s4, v254, 34
	v_readlane_b32 s5, v254, 35
	s_and_b64 s[4:5], s[4:5], exec
	s_cselect_b32 s4, s6, s7
	s_mul_i32 s7, s7, 12
	s_lshl_b32 s6, s4, 8
	s_sub_i32 s4, s2, s7
	s_lshl_b32 s7, s4, 8
	v_add_u32_e32 v3, s7, v164
	v_min_i32_e32 v3, 0xbff, v3
	v_lshl_or_b32 v6, v3, 10, v141
	v_add_u32_e32 v3, s7, v165
	v_min_i32_e32 v3, 0xbff, v3
	v_add_u32_e32 v2, s7, v139
	v_lshl_or_b32 v10, v3, 10, v141
	v_add_u32_e32 v3, s7, v166
	v_add_lshl_u32 v0, s6, v139, 10
	v_min_i32_e32 v2, 0xbff, v2
	v_min_i32_e32 v3, 0xbff, v3
	v_lshl_or_b32 v2, v2, 10, v141
	v_lshl_or_b32 v14, v3, 10, v141
	v_lshlrev_b64 v[16:17], 1, v[0:1]
	v_readfirstlane_b32 s4, v167
	v_mov_b32_e32 v3, v1
	v_add_lshl_u32 v4, s6, v164, 10
	v_lshl_add_u64 v[18:19], v[134:135], 0, v[16:17]
	s_mov_b32 m0, s4
	v_lshlrev_b64 v[2:3], 1, v[2:3]
	v_readfirstlane_b32 s4, v168
	v_mov_b32_e32 v5, v1
	s_waitcnt lgkmcnt(0)
	s_barrier
; DI void vm_wait0() { asm volatile("s_waitcnt vmcnt(0)" ::: "memory"); }
;   DI unsigned rowoff(int m) const { int combo = m >> 9, n = m & 511, b = combo >> 1, g = combo & 1; return (unsigned)((b * SEQ + 16 * n) * EIN + col0 + g * 64); }
;   DI unsigned koff(int k) const { return (unsigned)((k >> 6) * EIN + (k & 63)); }
; DI void dma16(const void* g, unsigned char* l) { __builtin_amdgcn_global_load_lds((const unsigned*)g, (lds_u32_t*)(unsigned)(size_t)l, 16, 0, 0); }
; template <class AF, class EF>
; DI void gemm_run(unsigned char* lds, int wv, const AF& af, const bf16_t* __restrict__ Bt, int ldb, int M, int N, int K, const EF& ef, int blk_off) {
;     ...
;     f32x4 acc[4][8];
; #pragma unroll
;     for (int i = 0; i < 4; ++i)
; #pragma unroll
;       for (int j = 0; j < 8; ++j) acc[i][j] = (f32x4){0.f, 0.f, 0.f, 0.f};
;     unsigned aoff[4], boff[4];
;     const bf16_t* Ab = af.base();
; #pragma unroll
;     for (int i = 0; i < 4; ++i) {
;       int row = crow + 64 * i;
;       aoff[i] = af.rowoff(m0 + row);
;       int n = n0 + row; n = n < N ? n : N - 1;
;       boff[i] = (unsigned)(n * ldb + cch);
;     }
;     __syncthreads();
; #pragma unroll
;     for (int i = 0; i < 4; ++i) {
;       dma16(Ab + aoff[i] + af.koff(cch), sBase + 32768 + (i * 512 + tid) * 16);
;       dma16(Bt + boff[i], sBase + (i * 512 + tid) * 16);
;     }
;     vm_wait0();
;     __syncthreads();
; #pragma unroll 1
;     for (int kt = 0; kt < nk; ++kt) {
;       unsigned char* cur = sBase + (kt & 1) * GST;
;       if (kt + 1 < nk) {
;         unsigned char* nxt = sBase + ((kt + 1) & 1) * GST;
;         const int k0 = (kt + 1) << 6;
; #pragma unroll
;         for (int i = 0; i < 4; ++i) {
;           dma16(Ab + aoff[i] + af.koff(k0 + cch), nxt + 32768 + (i * 512 + tid) * 16);
;           dma16(Bt + boff[i] + (unsigned)k0, nxt + (i * 512 + tid) * 16);
;         }
	global_load_lds_dwordx4 v[18:19], off
	v_lshl_add_u64 v[18:19], s[8:9], 0, v[2:3]
	s_mov_b32 m0, s4
	v_lshlrev_b64 v[4:5], 1, v[4:5]
	v_readfirstlane_b32 s4, v169
	v_mov_b32_e32 v7, v1
	v_add_lshl_u32 v8, s6, v165, 10
	global_load_lds_dwordx4 v[18:19], off
	v_lshl_add_u64 v[18:19], v[134:135], 0, v[4:5]
	s_mov_b32 m0, s4
	v_lshlrev_b64 v[6:7], 1, v[6:7]
	v_readfirstlane_b32 s4, v170
	v_mov_b32_e32 v9, v1
	global_load_lds_dwordx4 v[18:19], off
	v_lshl_add_u64 v[18:19], s[8:9], 0, v[6:7]
	s_mov_b32 m0, s4
	v_lshlrev_b64 v[8:9], 1, v[8:9]
	v_readfirstlane_b32 s4, v171
	v_mov_b32_e32 v11, v1
	v_add_lshl_u32 v12, s6, v166, 10
	global_load_lds_dwordx4 v[18:19], off
	v_lshl_add_u64 v[18:19], v[134:135], 0, v[8:9]
	s_mov_b32 m0, s4
	v_lshlrev_b64 v[10:11], 1, v[10:11]
	v_readfirstlane_b32 s4, v172
	v_mov_b32_e32 v13, v1
	global_load_lds_dwordx4 v[18:19], off
	v_lshl_add_u64 v[18:19], s[8:9], 0, v[10:11]
	s_mov_b32 m0, s4
	v_lshlrev_b64 v[12:13], 1, v[12:13]
	v_readfirstlane_b32 s4, v173
	v_mov_b32_e32 v15, v1
	global_load_lds_dwordx4 v[18:19], off
	v_lshl_add_u64 v[18:19], v[134:135], 0, v[12:13]
	s_mov_b32 m0, s4
	v_lshlrev_b64 v[14:15], 1, v[14:15]
	v_readfirstlane_b32 s4, v174
	global_load_lds_dwordx4 v[18:19], off
	v_lshl_add_u64 v[18:19], s[8:9], 0, v[14:15]
	s_mov_b32 m0, s4
	v_lshl_add_u64 v[152:153], s[12:13], 0, v[2:3]
	global_load_lds_dwordx4 v[18:19], off
	v_mov_b32_e32 v2, 0
	v_lshl_add_u64 v[146:147], s[12:13], 0, v[14:15]
	v_lshl_add_u64 v[148:149], s[12:13], 0, v[10:11]
	v_lshl_add_u64 v[150:151], s[12:13], 0, v[6:7]
	v_lshl_add_u64 v[154:155], v[144:145], 0, v[12:13]
	v_lshl_add_u64 v[156:157], v[144:145], 0, v[8:9]
	v_lshl_add_u64 v[158:159], v[144:145], 0, v[4:5]
	v_lshl_add_u64 v[160:161], v[144:145], 0, v[16:17]
	s_mov_b64 s[4:5], 0
	s_mov_b32 s14, 0x10000
	v_mov_b32_e32 v3, v2
	v_mov_b32_e32 v4, v2
	v_mov_b32_e32 v5, v2
	v_mov_b32_e32 v6, v2
	v_mov_b32_e32 v7, v2
	v_mov_b32_e32 v8, v2
	v_mov_b32_e32 v9, v2
	v_mov_b32_e32 v18, v2
	v_mov_b32_e32 v19, v2
	v_mov_b32_e32 v20, v2
	v_mov_b32_e32 v21, v2
	v_mov_b32_e32 v26, v2
	v_mov_b32_e32 v27, v2
	v_mov_b32_e32 v28, v2
	v_mov_b32_e32 v29, v2
	v_mov_b32_e32 v34, v2
	v_mov_b32_e32 v35, v2
	v_mov_b32_e32 v36, v2
	v_mov_b32_e32 v37, v2
	v_mov_b32_e32 v42, v2
	v_mov_b32_e32 v43, v2
	v_mov_b32_e32 v44, v2
	v_mov_b32_e32 v45, v2
	v_mov_b32_e32 v50, v2
	v_mov_b32_e32 v51, v2
	v_mov_b32_e32 v52, v2
	v_mov_b32_e32 v53, v2
	v_mov_b32_e32 v58, v2
	v_mov_b32_e32 v59, v2
	v_mov_b32_e32 v60, v2
	v_mov_b32_e32 v61, v2
	v_mov_b32_e32 v66, v2
	v_mov_b32_e32 v67, v2
	v_mov_b32_e32 v68, v2
	v_mov_b32_e32 v69, v2
	v_mov_b32_e32 v74, v2
	v_mov_b32_e32 v75, v2
	v_mov_b32_e32 v76, v2
	v_mov_b32_e32 v77, v2
	v_mov_b32_e32 v82, v2
	v_mov_b32_e32 v83, v2
	v_mov_b32_e32 v84, v2
	v_mov_b32_e32 v85, v2
	v_mov_b32_e32 v90, v2
	v_mov_b32_e32 v91, v2
	v_mov_b32_e32 v92, v2
	v_mov_b32_e32 v93, v2
	v_mov_b32_e32 v98, v2
	v_mov_b32_e32 v99, v2
	v_mov_b32_e32 v100, v2
	v_mov_b32_e32 v101, v2
	v_mov_b32_e32 v106, v2
	v_mov_b32_e32 v107, v2
	v_mov_b32_e32 v108, v2
	v_mov_b32_e32 v109, v2
	v_mov_b32_e32 v114, v2
	v_mov_b32_e32 v115, v2
	v_mov_b32_e32 v116, v2
	v_mov_b32_e32 v117, v2
	v_mov_b32_e32 v122, v2
	v_mov_b32_e32 v123, v2
	v_mov_b32_e32 v124, v2
	v_mov_b32_e32 v125, v2
	v_mov_b32_e32 v70, v2
	v_mov_b32_e32 v71, v2
	v_mov_b32_e32 v72, v2
	v_mov_b32_e32 v73, v2
	v_mov_b32_e32 v78, v2
	v_mov_b32_e32 v79, v2
	v_mov_b32_e32 v80, v2
	v_mov_b32_e32 v81, v2
	v_mov_b32_e32 v86, v2
	v_mov_b32_e32 v87, v2
	v_mov_b32_e32 v88, v2
	v_mov_b32_e32 v89, v2
	v_mov_b32_e32 v94, v2
	v_mov_b32_e32 v95, v2
	v_mov_b32_e32 v96, v2
	v_mov_b32_e32 v97, v2
	v_mov_b32_e32 v102, v2
	v_mov_b32_e32 v103, v2
	v_mov_b32_e32 v104, v2
	v_mov_b32_e32 v105, v2
	v_mov_b32_e32 v110, v2
	v_mov_b32_e32 v111, v2
	v_mov_b32_e32 v112, v2
	v_mov_b32_e32 v113, v2
	v_mov_b32_e32 v118, v2
	v_mov_b32_e32 v119, v2
	v_mov_b32_e32 v120, v2
	v_mov_b32_e32 v121, v2
	v_mov_b32_e32 v126, v2
	v_mov_b32_e32 v127, v2
	v_mov_b32_e32 v128, v2
	v_mov_b32_e32 v129, v2
	v_mov_b32_e32 v62, v2
	v_mov_b32_e32 v63, v2
	v_mov_b32_e32 v64, v2
	v_mov_b32_e32 v65, v2
	v_mov_b32_e32 v54, v2
	v_mov_b32_e32 v55, v2
	v_mov_b32_e32 v56, v2
	v_mov_b32_e32 v57, v2
	v_mov_b32_e32 v46, v2
	v_mov_b32_e32 v47, v2
	v_mov_b32_e32 v48, v2
	v_mov_b32_e32 v49, v2
	v_mov_b32_e32 v38, v2
	v_mov_b32_e32 v39, v2
	v_mov_b32_e32 v40, v2
	v_mov_b32_e32 v41, v2
	v_mov_b32_e32 v30, v2
	v_mov_b32_e32 v31, v2
	v_mov_b32_e32 v32, v2
	v_mov_b32_e32 v33, v2
	v_mov_b32_e32 v22, v2
	v_mov_b32_e32 v23, v2
	v_mov_b32_e32 v24, v2
	v_mov_b32_e32 v25, v2
	v_mov_b32_e32 v14, v2
	v_mov_b32_e32 v15, v2
	v_mov_b32_e32 v16, v2
	v_mov_b32_e32 v17, v2
	v_mov_b32_e32 v10, v2
	v_mov_b32_e32 v11, v2
	v_mov_b32_e32 v12, v2
	v_mov_b32_e32 v13, v2
	v_readlane_b32 s101, v254, 0
	s_nop 3
	s_lshr_b32 s101, s101, 8
	s_lshl_b32 s101, s101, 1
	s_and_b32 s15, s14, 0x10000
	s_add_i32 s15, s15, 0
	s_add_i32 s16, s15, 0x2000
	s_add_i32 s15, s15, 0xa000
	v_add_u32_e32 v224, s15, v136
	v_lshl_add_u64 v[222:223], v[160:161], 0, s[4:5]
	v_readfirstlane_b32 s17, v224
	v_add_u32_e32 v224, s16, v136
	s_mov_b32 m0, s17
	v_readfirstlane_b32 s17, v224
	v_add_u32_e32 v224, s15, v138
	global_load_lds_dwordx4 v[222:223], off
	v_lshl_add_u64 v[222:223], v[152:153], 0, s[4:5]
	s_mov_b32 m0, s17
	v_readfirstlane_b32 s17, v224
	v_add_u32_e32 v224, s16, v138
	global_load_lds_dwordx4 v[222:223], off
	v_lshl_add_u64 v[222:223], v[158:159], 0, s[4:5]
	s_mov_b32 m0, s17
	v_readfirstlane_b32 s17, v224
	v_add_u32_e32 v224, s15, v140
	global_load_lds_dwordx4 v[222:223], off
	v_lshl_add_u64 v[222:223], v[150:151], 0, s[4:5]
	s_mov_b32 m0, s17
	v_readfirstlane_b32 s17, v224
	v_add_u32_e32 v224, s16, v140
	global_load_lds_dwordx4 v[222:223], off
	v_lshl_add_u64 v[222:223], v[156:157], 0, s[4:5]
	s_mov_b32 m0, s17
	v_readfirstlane_b32 s17, v224
	v_add_u32_e32 v224, s15, v142
	global_load_lds_dwordx4 v[222:223], off
	v_lshl_add_u64 v[222:223], v[148:149], 0, s[4:5]
	s_mov_b32 m0, s17
	v_readfirstlane_b32 s15, v224
	v_add_u32_e32 v224, s16, v142
	global_load_lds_dwordx4 v[222:223], off
	v_lshl_add_u64 v[222:223], v[154:155], 0, s[4:5]
	s_mov_b32 m0, s15
	v_readfirstlane_b32 s15, v224
	global_load_lds_dwordx4 v[222:223], off
	v_lshl_add_u64 v[222:223], v[146:147], 0, s[4:5]
	s_mov_b32 m0, s15
	s_nop 0
	global_load_lds_dwordx4 v[222:223], off
	s_waitcnt vmcnt(8) lgkmcnt(0)
	s_barrier
	s_branch .LBB0_121

; #define MFMA16(a, b, c) __builtin_amdgcn_mfma_f32_16x16x32_bf16((a), (b), (c), 0, 0, 0)
;   DI unsigned koff(int k) const { return (unsigned)((k >> 6) * EIN + (k & 63)); }
; DI void dma16(const void* g, unsigned char* l) { __builtin_amdgcn_global_load_lds((const unsigned*)g, (lds_u32_t*)(unsigned)(size_t)l, 16, 0, 0); }
; template <class AF, class EF>
; DI void gemm_run(unsigned char* lds, int wv, const AF& af, const bf16_t* __restrict__ Bt, int ldb, int M, int N, int K, const EF& ef, int blk_off) {
;     ...
;       if (kt + 1 < nk) {
;         unsigned char* nxt = sBase + ((kt + 1) & 1) * GST;
;         const int k0 = (kt + 1) << 6;
; #pragma unroll
;         for (int i = 0; i < 4; ++i) {
;           dma16(Ab + aoff[i] + af.koff(k0 + cch), nxt + 32768 + (i * 512 + tid) * 16);
;           dma16(Bt + boff[i] + (unsigned)k0, nxt + (i * 512 + tid) * 16);
;         }
;       }
; #pragma unroll
;       for (int ks = 0; ks < 2; ++ks) {
;         bf16x8 wf[4], xf[8];
; #pragma unroll
;         for (int i = 0; i < 4; ++i) wf[i] = *(const bf16x8*)(cur + (wn * 64 + i * 16 + l15) * 128 + (((ks * 4 + q4) ^ swz) * 16));
; #pragma unroll
;         for (int j = 0; j < 8; ++j) xf[j] = *(const bf16x8*)(cur + 32768 + (wm * 128 + j * 16 + l15) * 128 + (((ks * 4 + q4) ^ swz) * 16));
; #pragma unroll
;         for (int i = 0; i < 4; ++i)
; #pragma unroll
;           for (int j = 0; j < 8; ++j) acc[i][j] = MFMA16(wf[i], xf[j], acc[i][j]);
;       }
.Lmyg120_loop:
	s_waitcnt lgkmcnt(7)
	v_mfma_f32_16x16x32_bf16 v[126:129], v[130:133], v[180:183], v[126:129]
	ds_read_b128 v[226:229], v212 offset:10240
	s_waitcnt lgkmcnt(7)
	v_mfma_f32_16x16x32_bf16 v[118:121], v[130:133], v[184:187], v[118:121]
	s_waitcnt lgkmcnt(6)
	v_mfma_f32_16x16x32_bf16 v[110:113], v[130:133], v[188:191], v[110:113]
	s_waitcnt lgkmcnt(5)
	v_mfma_f32_16x16x32_bf16 v[102:105], v[130:133], v[192:195], v[102:105]
	s_waitcnt lgkmcnt(4)
	v_mfma_f32_16x16x32_bf16 v[94:97], v[130:133], v[196:199], v[94:97]
	s_waitcnt lgkmcnt(3)
	v_mfma_f32_16x16x32_bf16 v[86:89], v[130:133], v[200:203], v[86:89]
	s_waitcnt lgkmcnt(2)
	v_mfma_f32_16x16x32_bf16 v[78:81], v[130:133], v[204:207], v[78:81]
	s_waitcnt lgkmcnt(1)
	v_mfma_f32_16x16x32_bf16 v[70:73], v[130:133], v[208:211], v[70:73]
	s_waitcnt lgkmcnt(0)
	v_mfma_f32_16x16x32_bf16 v[122:125], v[226:229], v[180:183], v[122:125]
	ds_read_b128 v[130:133], v212 offset:12288
	v_mfma_f32_16x16x32_bf16 v[114:117], v[226:229], v[184:187], v[114:117]
	v_mfma_f32_16x16x32_bf16 v[106:109], v[226:229], v[188:191], v[106:109]
	v_mfma_f32_16x16x32_bf16 v[98:101], v[226:229], v[192:195], v[98:101]
	v_mfma_f32_16x16x32_bf16 v[90:93], v[226:229], v[196:199], v[90:93]
	v_mfma_f32_16x16x32_bf16 v[82:85], v[226:229], v[200:203], v[82:85]
	v_mfma_f32_16x16x32_bf16 v[74:77], v[226:229], v[204:207], v[74:77]
	v_mfma_f32_16x16x32_bf16 v[66:69], v[226:229], v[208:211], v[66:69]
	s_bitcmp1_b32 s101, 0
	s_cbranch_scc0 .Lmyg120_noB
	s_andn2_b32 s101, s101, 1
	s_setprio 3
	s_and_b32 s15, s14, 0x10000
	s_add_i32 s15, s15, 0
	s_add_i32 s16, s15, 0x2000
	s_add_i32 s15, s15, 0xa000
	v_add_u32_e32 v224, s15, v136
	v_lshl_add_u64 v[222:223], v[160:161], 0, s[4:5]
	v_readfirstlane_b32 s17, v224
	v_add_u32_e32 v224, s16, v136
	s_mov_b32 m0, s17
	v_readfirstlane_b32 s17, v224
	v_add_u32_e32 v224, s15, v138
	global_load_lds_dwordx4 v[222:223], off
	v_lshl_add_u64 v[222:223], v[152:153], 0, s[4:5]
	s_mov_b32 m0, s17
	v_readfirstlane_b32 s17, v224
	v_add_u32_e32 v224, s16, v138
	global_load_lds_dwordx4 v[222:223], off
	v_lshl_add_u64 v[222:223], v[158:159], 0, s[4:5]
	s_mov_b32 m0, s17
	v_readfirstlane_b32 s17, v224
	v_add_u32_e32 v224, s15, v140
	global_load_lds_dwordx4 v[222:223], off
	v_lshl_add_u64 v[222:223], v[150:151], 0, s[4:5]
	s_mov_b32 m0, s17
	v_readfirstlane_b32 s17, v224
	v_add_u32_e32 v224, s16, v140
	global_load_lds_dwordx4 v[222:223], off
	v_lshl_add_u64 v[222:223], v[156:157], 0, s[4:5]
	s_mov_b32 m0, s17
	v_readfirstlane_b32 s17, v224
	v_add_u32_e32 v224, s15, v142
	global_load_lds_dwordx4 v[222:223], off
	v_lshl_add_u64 v[222:223], v[148:149], 0, s[4:5]
	s_mov_b32 m0, s17
	v_readfirstlane_b32 s15, v224
	v_add_u32_e32 v224, s16, v142
	global_load_lds_dwordx4 v[222:223], off
	v_lshl_add_u64 v[222:223], v[154:155], 0, s[4:5]
	s_mov_b32 m0, s15
	v_readfirstlane_b32 s15, v224
	global_load_lds_dwordx4 v[222:223], off
	v_lshl_add_u64 v[222:223], v[146:147], 0, s[4:5]
	s_mov_b32 m0, s15
	s_nop 0
	global_load_lds_dwordx4 v[222:223], off
	s_setprio 0
; #define MFMA16(a, b, c) __builtin_amdgcn_mfma_f32_16x16x32_bf16((a), (b), (c), 0, 0, 0)
; DI void vm_wait0() { asm volatile("s_waitcnt vmcnt(0)" ::: "memory"); }
;   DI unsigned koff(int k) const { return (unsigned)((k >> 6) * EIN + (k & 63)); }
; DI void dma16(const void* g, unsigned char* l) { __builtin_amdgcn_global_load_lds((const unsigned*)g, (lds_u32_t*)(unsigned)(size_t)l, 16, 0, 0); }
; template <class AF, class EF>
; DI void gemm_run(unsigned char* lds, int wv, const AF& af, const bf16_t* __restrict__ Bt, int ldb, int M, int N, int K, const EF& ef, int blk_off) {
;     ...
;       if (kt + 1 < nk) {
;         unsigned char* nxt = sBase + ((kt + 1) & 1) * GST;
;         const int k0 = (kt + 1) << 6;
; #pragma unroll
;         for (int i = 0; i < 4; ++i) {
;           dma16(Ab + aoff[i] + af.koff(k0 + cch), nxt + 32768 + (i * 512 + tid) * 16);
;           dma16(Bt + boff[i] + (unsigned)k0, nxt + (i * 512 + tid) * 16);
;         }
;     ...
; #pragma unroll
;       for (int ks = 0; ks < 2; ++ks) {
;         bf16x8 wf[4], xf[8];
; #pragma unroll
;         for (int i = 0; i < 4; ++i) wf[i] = *(const bf16x8*)(cur + (wn * 64 + i * 16 + l15) * 128 + (((ks * 4 + q4) ^ swz) * 16));
; #pragma unroll
;         for (int j = 0; j < 8; ++j) xf[j] = *(const bf16x8*)(cur + 32768 + (wm * 128 + j * 16 + l15) * 128 + (((ks * 4 + q4) ^ swz) * 16));
; #pragma unroll
;         for (int i = 0; i < 4; ++i)
; #pragma unroll
;           for (int j = 0; j < 8; ++j) acc[i][j] = MFMA16(wf[i], xf[j], acc[i][j]);
;       }
;       vm_wait0();
;       __syncthreads();
;     }
.Lmyg120_noB:
	s_waitcnt lgkmcnt(0)
	v_mfma_f32_16x16x32_bf16 v[58:61], v[130:133], v[180:183], v[58:61]
	ds_read_b128 v[226:229], v212 offset:14336
	v_mfma_f32_16x16x32_bf16 v[50:53], v[130:133], v[184:187], v[50:53]
	v_add_u32_e32 v0, s100, v179
	v_mfma_f32_16x16x32_bf16 v[42:45], v[130:133], v[188:191], v[42:45]
	v_add3_u32 v212, v0, v176, v177
	v_mfma_f32_16x16x32_bf16 v[34:37], v[130:133], v[192:195], v[34:37]
	v_add3_u32 v0, v0, v178, v177
	v_mfma_f32_16x16x32_bf16 v[26:29], v[130:133], v[196:199], v[26:29]
	v_mfma_f32_16x16x32_bf16 v[18:21], v[130:133], v[200:203], v[18:21]
	v_mfma_f32_16x16x32_bf16 v[6:9], v[130:133], v[204:207], v[6:9]
	v_mfma_f32_16x16x32_bf16 v[2:5], v[130:133], v[208:211], v[2:5]
	s_waitcnt lgkmcnt(0)
	v_mfma_f32_16x16x32_bf16 v[62:65], v[226:229], v[180:183], v[62:65]
	ds_read_b128 v[130:133], v212 offset:8192
	ds_read_b128 v[180:183], v0 offset:40960
	v_mfma_f32_16x16x32_bf16 v[54:57], v[226:229], v[184:187], v[54:57]
	ds_read_b128 v[184:187], v0 offset:43008
	v_mfma_f32_16x16x32_bf16 v[46:49], v[226:229], v[188:191], v[46:49]
	ds_read_b128 v[188:191], v0 offset:45056
	v_mfma_f32_16x16x32_bf16 v[38:41], v[226:229], v[192:195], v[38:41]
	ds_read_b128 v[192:195], v0 offset:47104
	v_mfma_f32_16x16x32_bf16 v[30:33], v[226:229], v[196:199], v[30:33]
	ds_read_b128 v[196:199], v0 offset:49152
	v_mfma_f32_16x16x32_bf16 v[22:25], v[226:229], v[200:203], v[22:25]
	ds_read_b128 v[200:203], v0 offset:51200
	v_mfma_f32_16x16x32_bf16 v[14:17], v[226:229], v[204:207], v[14:17]
	ds_read_b128 v[204:207], v0 offset:53248
	v_mfma_f32_16x16x32_bf16 v[10:13], v[226:229], v[208:211], v[10:13]
	ds_read_b128 v[208:211], v0 offset:55296
	s_waitcnt lgkmcnt(7)
	v_mfma_f32_16x16x32_bf16 v[126:129], v[130:133], v[180:183], v[126:129]
	ds_read_b128 v[226:229], v212 offset:10240
	s_waitcnt lgkmcnt(7)
	v_mfma_f32_16x16x32_bf16 v[118:121], v[130:133], v[184:187], v[118:121]
	s_waitcnt lgkmcnt(6)
	v_mfma_f32_16x16x32_bf16 v[110:113], v[130:133], v[188:191], v[110:113]
	s_waitcnt lgkmcnt(5)
	v_mfma_f32_16x16x32_bf16 v[102:105], v[130:133], v[192:195], v[102:105]
	s_waitcnt lgkmcnt(4)
	v_mfma_f32_16x16x32_bf16 v[94:97], v[130:133], v[196:199], v[94:97]
	s_waitcnt lgkmcnt(3)
	v_mfma_f32_16x16x32_bf16 v[86:89], v[130:133], v[200:203], v[86:89]
	s_waitcnt lgkmcnt(2)
	v_mfma_f32_16x16x32_bf16 v[78:81], v[130:133], v[204:207], v[78:81]
	s_waitcnt lgkmcnt(1)
	v_mfma_f32_16x16x32_bf16 v[70:73], v[130:133], v[208:211], v[70:73]
	s_waitcnt lgkmcnt(0)
	v_mfma_f32_16x16x32_bf16 v[122:125], v[226:229], v[180:183], v[122:125]
	ds_read_b128 v[130:133], v212 offset:12288
	v_mfma_f32_16x16x32_bf16 v[114:117], v[226:229], v[184:187], v[114:117]
	v_mfma_f32_16x16x32_bf16 v[106:109], v[226:229], v[188:191], v[106:109]
	v_mfma_f32_16x16x32_bf16 v[98:101], v[226:229], v[192:195], v[98:101]
	v_mfma_f32_16x16x32_bf16 v[90:93], v[226:229], v[196:199], v[90:93]
	v_mfma_f32_16x16x32_bf16 v[82:85], v[226:229], v[200:203], v[82:85]
	v_mfma_f32_16x16x32_bf16 v[74:77], v[226:229], v[204:207], v[74:77]
	v_mfma_f32_16x16x32_bf16 v[66:69], v[226:229], v[208:211], v[66:69]
	s_waitcnt lgkmcnt(0)
	v_mfma_f32_16x16x32_bf16 v[58:61], v[130:133], v[180:183], v[58:61]
	ds_read_b128 v[226:229], v212 offset:14336
	v_mfma_f32_16x16x32_bf16 v[50:53], v[130:133], v[184:187], v[50:53]
	v_mfma_f32_16x16x32_bf16 v[42:45], v[130:133], v[188:191], v[42:45]
	v_mfma_f32_16x16x32_bf16 v[34:37], v[130:133], v[192:195], v[34:37]
	v_mfma_f32_16x16x32_bf16 v[26:29], v[130:133], v[196:199], v[26:29]
	v_mfma_f32_16x16x32_bf16 v[18:21], v[130:133], v[200:203], v[18:21]
	v_mfma_f32_16x16x32_bf16 v[6:9], v[130:133], v[204:207], v[6:9]
	v_mfma_f32_16x16x32_bf16 v[2:5], v[130:133], v[208:211], v[2:5]
	s_waitcnt vmcnt(0) lgkmcnt(0)
	s_barrier
	s_add_u32 s4, s4, 0x80
	s_addc_u32 s5, s5, 0
	s_add_i32 s14, s14, 0x10000
	s_cmpk_eq_i32 s4, 0x800
	s_cbranch_scc1 .Lmyg120_tail
	s_add_i32 s100, s14, 0xffff0000
	s_and_b32 s100, s100, 0x10000
	v_add_u32_e32 v0, s100, v175
	v_add3_u32 v212, v0, v176, v177
	v_add3_u32 v0, v0, v178, v177
	s_cmpk_eq_i32 s4, 0x780
	s_cbranch_scc1 .Lmyg120_nodma
	s_bitcmp1_b32 s101, 1
	s_cbranch_scc1 .Lmyg120_defer
	s_setprio 3
	s_and_b32 s15, s14, 0x10000
	s_add_i32 s15, s15, 0
	s_add_i32 s16, s15, 0x2000
	s_add_i32 s15, s15, 0xa000
	v_add_u32_e32 v224, s15, v136
	v_lshl_add_u64 v[222:223], v[160:161], 0, s[4:5]
	v_readfirstlane_b32 s17, v224
	v_add_u32_e32 v224, s16, v136
	s_mov_b32 m0, s17
	v_readfirstlane_b32 s17, v224
	v_add_u32_e32 v224, s15, v138
	global_load_lds_dwordx4 v[222:223], off
	v_lshl_add_u64 v[222:223], v[152:153], 0, s[4:5]
	s_mov_b32 m0, s17
	v_readfirstlane_b32 s17, v224
	v_add_u32_e32 v224, s16, v138
	global_load_lds_dwordx4 v[222:223], off
	v_lshl_add_u64 v[222:223], v[158:159], 0, s[4:5]
	s_mov_b32 m0, s17
	v_readfirstlane_b32 s17, v224
	v_add_u32_e32 v224, s15, v140
	global_load_lds_dwordx4 v[222:223], off
	v_lshl_add_u64 v[222:223], v[150:151], 0, s[4:5]
	s_mov_b32 m0, s17
	v_readfirstlane_b32 s17, v224
	v_add_u32_e32 v224, s16, v140
	global_load_lds_dwordx4 v[222:223], off
	v_lshl_add_u64 v[222:223], v[156:157], 0, s[4:5]
	s_mov_b32 m0, s17
	v_readfirstlane_b32 s17, v224
	v_add_u32_e32 v224, s15, v142
	global_load_lds_dwordx4 v[222:223], off
	v_lshl_add_u64 v[222:223], v[148:149], 0, s[4:5]
	s_mov_b32 m0, s17
	v_readfirstlane_b32 s15, v224
	v_add_u32_e32 v224, s16, v142
	global_load_lds_dwordx4 v[222:223], off
	v_lshl_add_u64 v[222:223], v[154:155], 0, s[4:5]
	s_mov_b32 m0, s15
	v_readfirstlane_b32 s15, v224
	global_load_lds_dwordx4 v[222:223], off
	v_lshl_add_u64 v[222:223], v[146:147], 0, s[4:5]
	s_mov_b32 m0, s15
	s_nop 0
	global_load_lds_dwordx4 v[222:223], off
	s_setprio 0
	s_branch .Lmyg120_nodma
.Lmyg120_defer:
	s_or_b32 s101, s101, 1

;   DI unsigned rowoff(int m) const { int combo = m >> 9, n = m & 511, b = combo >> 1, g = combo & 1; return (unsigned)((b * SEQ + 16 * n) * EIN + col0 + g * 64); }
;   DI unsigned koff(int k) const { return (unsigned)((k >> 6) * EIN + (k & 63)); }
; DI void dma16(const void* g, unsigned char* l) { __builtin_amdgcn_global_load_lds((const unsigned*)g, (lds_u32_t*)(unsigned)(size_t)l, 16, 0, 0); }
; template <class AF, class EF>
; DI void gemm_run(unsigned char* lds, int wv, const AF& af, const bf16_t* __restrict__ Bt, int ldb, int M, int N, int K, const EF& ef, int blk_off) {
;     ...
;   for (int tile_ = first; tile_ < ntl_eff; tile_ += tstep) {
;     int nt, mt;
;     if (xmap) { nt = tile_ % ntiles; mt = (tile_ / ntiles) * 8 + ((int)blockIdx.x & 7); }
;     else { nt = tile_ % ntiles; mt = tile_ / ntiles; }
;     const int m0 = mt << 8, n0 = nt << 8;
;     f32x4 acc[4][8];
; #pragma unroll
;     for (int i = 0; i < 4; ++i)
; #pragma unroll
;       for (int j = 0; j < 8; ++j) acc[i][j] = (f32x4){0.f, 0.f, 0.f, 0.f};
;     unsigned aoff[4], boff[4];
;     const bf16_t* Ab = af.base();
; #pragma unroll
;     for (int i = 0; i < 4; ++i) {
;       int row = crow + 64 * i;
;       aoff[i] = af.rowoff(m0 + row);
;       int n = n0 + row; n = n < N ? n : N - 1;
;       boff[i] = (unsigned)(n * ldb + cch);
;     }
;     __syncthreads();
; #pragma unroll
;     for (int i = 0; i < 4; ++i) {
;       dma16(Ab + aoff[i] + af.koff(cch), sBase + 32768 + (i * 512 + tid) * 16);
;       dma16(Bt + boff[i], sBase + (i * 512 + tid) * 16);
;     }
.LBB0_260:
	s_mul_hi_i32 s4, s2, 0x66666667
	s_lshr_b32 s5, s4, 31
	s_ashr_i32 s4, s4, 2
	s_add_i32 s6, s4, s5
	s_lshl_b32 s4, s6, 3
	s_or_b32 s7, s4, s78
	v_readlane_b32 s4, v254, 34
	v_readlane_b32 s5, v254, 35
	s_and_b64 s[4:5], s[4:5], exec
	s_cselect_b32 s4, s7, s6
	s_mul_i32 s6, s6, 10
	s_lshl_b32 s7, s4, 8
	s_sub_i32 s4, s2, s6
	s_lshl_b32 s6, s4, 8
	v_add_u32_e32 v3, s6, v164
	v_min_i32_e32 v3, 0x9df, v3
	v_lshl_or_b32 v6, v3, 10, v141
	v_add_u32_e32 v3, s6, v165
	v_min_i32_e32 v3, 0x9df, v3
	v_add_u32_e32 v2, s6, v139
	v_lshl_or_b32 v10, v3, 10, v141
	v_add_u32_e32 v3, s6, v166
	v_add_lshl_u32 v0, s7, v139, 10
	v_min_i32_e32 v2, 0x9df, v2
	v_min_i32_e32 v3, 0x9df, v3
	v_lshl_or_b32 v2, v2, 10, v141
	v_lshl_or_b32 v14, v3, 10, v141
	v_lshlrev_b64 v[16:17], 1, v[0:1]
	v_readfirstlane_b32 s4, v167
	v_mov_b32_e32 v3, v1
	v_add_lshl_u32 v4, s7, v164, 10
	v_lshl_add_u64 v[18:19], v[134:135], 0, v[16:17]
	s_mov_b32 m0, s4
	v_lshlrev_b64 v[2:3], 1, v[2:3]
	v_readfirstlane_b32 s4, v168
	v_mov_b32_e32 v5, v1
	s_waitcnt lgkmcnt(0)
	s_barrier
; DI void vm_wait0() { asm volatile("s_waitcnt vmcnt(0)" ::: "memory"); }
;   DI unsigned rowoff(int m) const { int combo = m >> 9, n = m & 511, b = combo >> 1, g = combo & 1; return (unsigned)((b * SEQ + 16 * n) * EIN + col0 + g * 64); }
;   DI unsigned koff(int k) const { return (unsigned)((k >> 6) * EIN + (k & 63)); }
; DI void dma16(const void* g, unsigned char* l) { __builtin_amdgcn_global_load_lds((const unsigned*)g, (lds_u32_t*)(unsigned)(size_t)l, 16, 0, 0); }
; template <class AF, class EF>
; DI void gemm_run(unsigned char* lds, int wv, const AF& af, const bf16_t* __restrict__ Bt, int ldb, int M, int N, int K, const EF& ef, int blk_off) {
;     ...
;     f32x4 acc[4][8];
; #pragma unroll
;     for (int i = 0; i < 4; ++i)
; #pragma unroll
;       for (int j = 0; j < 8; ++j) acc[i][j] = (f32x4){0.f, 0.f, 0.f, 0.f};
;     unsigned aoff[4], boff[4];
;     const bf16_t* Ab = af.base();
; #pragma unroll
;     for (int i = 0; i < 4; ++i) {
;       int row = crow + 64 * i;
;       aoff[i] = af.rowoff(m0 + row);
;       int n = n0 + row; n = n < N ? n : N - 1;
;       boff[i] = (unsigned)(n * ldb + cch);
;     }
;     __syncthreads();
; #pragma unroll
;     for (int i = 0; i < 4; ++i) {
;       dma16(Ab + aoff[i] + af.koff(cch), sBase + 32768 + (i * 512 + tid) * 16);
;       dma16(Bt + boff[i], sBase + (i * 512 + tid) * 16);
;     }
;     vm_wait0();
;     __syncthreads();
; #pragma unroll 1
;     for (int kt = 0; kt < nk; ++kt) {
;       unsigned char* cur = sBase + (kt & 1) * GST;
;       if (kt + 1 < nk) {
;         unsigned char* nxt = sBase + ((kt + 1) & 1) * GST;
;         const int k0 = (kt + 1) << 6;
; #pragma unroll
;         for (int i = 0; i < 4; ++i) {
;           dma16(Ab + aoff[i] + af.koff(k0 + cch), nxt + 32768 + (i * 512 + tid) * 16);
;           dma16(Bt + boff[i] + (unsigned)k0, nxt + (i * 512 + tid) * 16);
;         }
	global_load_lds_dwordx4 v[18:19], off
	v_lshl_add_u64 v[18:19], s[8:9], 0, v[2:3]
	s_mov_b32 m0, s4
	v_lshlrev_b64 v[4:5], 1, v[4:5]
	v_readfirstlane_b32 s4, v169
	v_mov_b32_e32 v7, v1
	v_add_lshl_u32 v8, s7, v165, 10
	global_load_lds_dwordx4 v[18:19], off
	v_lshl_add_u64 v[18:19], v[134:135], 0, v[4:5]
	s_mov_b32 m0, s4
	v_lshlrev_b64 v[6:7], 1, v[6:7]
	v_readfirstlane_b32 s4, v170
	v_mov_b32_e32 v9, v1
	global_load_lds_dwordx4 v[18:19], off
	v_lshl_add_u64 v[18:19], s[8:9], 0, v[6:7]
	s_mov_b32 m0, s4
	v_lshlrev_b64 v[8:9], 1, v[8:9]
	v_readfirstlane_b32 s4, v171
	v_mov_b32_e32 v11, v1
	v_add_lshl_u32 v12, s7, v166, 10
	global_load_lds_dwordx4 v[18:19], off
	v_lshl_add_u64 v[18:19], v[134:135], 0, v[8:9]
	s_mov_b32 m0, s4
	v_lshlrev_b64 v[10:11], 1, v[10:11]
	v_readfirstlane_b32 s4, v172
	v_mov_b32_e32 v13, v1
	global_load_lds_dwordx4 v[18:19], off
	v_lshl_add_u64 v[18:19], s[8:9], 0, v[10:11]
	s_mov_b32 m0, s4
	v_lshlrev_b64 v[12:13], 1, v[12:13]
	v_readfirstlane_b32 s4, v173
	v_mov_b32_e32 v15, v1
	global_load_lds_dwordx4 v[18:19], off
	v_lshl_add_u64 v[18:19], v[134:135], 0, v[12:13]
	s_mov_b32 m0, s4
	v_lshlrev_b64 v[14:15], 1, v[14:15]
	v_readfirstlane_b32 s4, v174
	global_load_lds_dwordx4 v[18:19], off
	v_lshl_add_u64 v[18:19], s[8:9], 0, v[14:15]
	s_mov_b32 m0, s4
	v_lshl_add_u64 v[152:153], s[14:15], 0, v[2:3]
	global_load_lds_dwordx4 v[18:19], off
	v_mov_b32_e32 v2, 0
	v_lshl_add_u64 v[146:147], s[14:15], 0, v[14:15]
	v_lshl_add_u64 v[148:149], s[14:15], 0, v[10:11]
	v_lshl_add_u64 v[150:151], s[14:15], 0, v[6:7]
	v_lshl_add_u64 v[154:155], v[144:145], 0, v[12:13]
	v_lshl_add_u64 v[156:157], v[144:145], 0, v[8:9]
	v_lshl_add_u64 v[158:159], v[144:145], 0, v[4:5]
	v_lshl_add_u64 v[160:161], v[144:145], 0, v[16:17]
	s_mov_b64 s[4:5], 0
	s_mov_b32 s16, 0x10000
	v_mov_b32_e32 v3, v2
	v_mov_b32_e32 v4, v2
	v_mov_b32_e32 v5, v2
	v_mov_b32_e32 v14, v2
	v_mov_b32_e32 v15, v2
	v_mov_b32_e32 v16, v2
	v_mov_b32_e32 v17, v2
	v_mov_b32_e32 v22, v2
	v_mov_b32_e32 v23, v2
	v_mov_b32_e32 v24, v2
	v_mov_b32_e32 v25, v2
	v_mov_b32_e32 v30, v2
	v_mov_b32_e32 v31, v2
	v_mov_b32_e32 v32, v2
	v_mov_b32_e32 v33, v2
	v_mov_b32_e32 v38, v2
	v_mov_b32_e32 v39, v2
	v_mov_b32_e32 v40, v2
	v_mov_b32_e32 v41, v2
	v_mov_b32_e32 v46, v2
	v_mov_b32_e32 v47, v2
	v_mov_b32_e32 v48, v2
	v_mov_b32_e32 v49, v2
	v_mov_b32_e32 v54, v2
	v_mov_b32_e32 v55, v2
	v_mov_b32_e32 v56, v2
	v_mov_b32_e32 v57, v2
	v_mov_b32_e32 v62, v2
	v_mov_b32_e32 v63, v2
	v_mov_b32_e32 v64, v2
	v_mov_b32_e32 v65, v2
	v_mov_b32_e32 v66, v2
	v_mov_b32_e32 v67, v2
	v_mov_b32_e32 v68, v2
	v_mov_b32_e32 v69, v2
	v_mov_b32_e32 v74, v2
	v_mov_b32_e32 v75, v2
	v_mov_b32_e32 v76, v2
	v_mov_b32_e32 v77, v2
	v_mov_b32_e32 v82, v2
	v_mov_b32_e32 v83, v2
	v_mov_b32_e32 v84, v2
	v_mov_b32_e32 v85, v2
	v_mov_b32_e32 v90, v2
	v_mov_b32_e32 v91, v2
	v_mov_b32_e32 v92, v2
	v_mov_b32_e32 v93, v2
	v_mov_b32_e32 v98, v2
	v_mov_b32_e32 v99, v2
	v_mov_b32_e32 v100, v2
	v_mov_b32_e32 v101, v2
	v_mov_b32_e32 v106, v2
	v_mov_b32_e32 v107, v2
	v_mov_b32_e32 v108, v2
	v_mov_b32_e32 v109, v2
	v_mov_b32_e32 v114, v2
	v_mov_b32_e32 v115, v2
	v_mov_b32_e32 v116, v2
	v_mov_b32_e32 v117, v2
	v_mov_b32_e32 v122, v2
	v_mov_b32_e32 v123, v2
	v_mov_b32_e32 v124, v2
	v_mov_b32_e32 v125, v2
	v_mov_b32_e32 v70, v2
	v_mov_b32_e32 v71, v2
	v_mov_b32_e32 v72, v2
	v_mov_b32_e32 v73, v2
	v_mov_b32_e32 v78, v2
	v_mov_b32_e32 v79, v2
	v_mov_b32_e32 v80, v2
	v_mov_b32_e32 v81, v2
	v_mov_b32_e32 v86, v2
	v_mov_b32_e32 v87, v2
	v_mov_b32_e32 v88, v2
	v_mov_b32_e32 v89, v2
	v_mov_b32_e32 v94, v2
	v_mov_b32_e32 v95, v2
	v_mov_b32_e32 v96, v2
	v_mov_b32_e32 v97, v2
	v_mov_b32_e32 v102, v2
	v_mov_b32_e32 v103, v2
	v_mov_b32_e32 v104, v2
	v_mov_b32_e32 v105, v2
	v_mov_b32_e32 v110, v2
	v_mov_b32_e32 v111, v2
	v_mov_b32_e32 v112, v2
	v_mov_b32_e32 v113, v2
	v_mov_b32_e32 v118, v2
	v_mov_b32_e32 v119, v2
	v_mov_b32_e32 v120, v2
	v_mov_b32_e32 v121, v2
	v_mov_b32_e32 v126, v2
	v_mov_b32_e32 v127, v2
	v_mov_b32_e32 v128, v2
	v_mov_b32_e32 v129, v2
	v_mov_b32_e32 v58, v2
	v_mov_b32_e32 v59, v2
	v_mov_b32_e32 v60, v2
	v_mov_b32_e32 v61, v2
	v_mov_b32_e32 v50, v2
	v_mov_b32_e32 v51, v2
	v_mov_b32_e32 v52, v2
	v_mov_b32_e32 v53, v2
	v_mov_b32_e32 v42, v2
	v_mov_b32_e32 v43, v2
	v_mov_b32_e32 v44, v2
	v_mov_b32_e32 v45, v2
	v_mov_b32_e32 v34, v2
	v_mov_b32_e32 v35, v2
	v_mov_b32_e32 v36, v2
	v_mov_b32_e32 v37, v2
	v_mov_b32_e32 v26, v2
	v_mov_b32_e32 v27, v2
	v_mov_b32_e32 v28, v2
	v_mov_b32_e32 v29, v2
	v_mov_b32_e32 v18, v2
	v_mov_b32_e32 v19, v2
	v_mov_b32_e32 v20, v2
	v_mov_b32_e32 v21, v2
	v_mov_b32_e32 v10, v2
	v_mov_b32_e32 v11, v2
	v_mov_b32_e32 v12, v2
	v_mov_b32_e32 v13, v2
	v_mov_b32_e32 v6, v2
	v_mov_b32_e32 v7, v2
	v_mov_b32_e32 v8, v2
	v_mov_b32_e32 v9, v2
	v_readlane_b32 s101, v254, 0
	s_nop 3
	s_lshr_b32 s101, s101, 8
	s_lshl_b32 s101, s101, 1
	s_and_b32 s17, s16, 0x10000
	s_add_i32 s17, s17, 0
	s_add_i32 s18, s17, 0x2000
	s_add_i32 s17, s17, 0xa000
	v_add_u32_e32 v224, s17, v136
	v_lshl_add_u64 v[222:223], v[160:161], 0, s[4:5]
	v_readfirstlane_b32 s19, v224
	v_add_u32_e32 v224, s18, v136
	s_mov_b32 m0, s19
	v_readfirstlane_b32 s19, v224
	v_add_u32_e32 v224, s17, v138
	global_load_lds_dwordx4 v[222:223], off
	v_lshl_add_u64 v[222:223], v[152:153], 0, s[4:5]
	s_mov_b32 m0, s19
	v_readfirstlane_b32 s19, v224
	v_add_u32_e32 v224, s18, v138
	global_load_lds_dwordx4 v[222:223], off
	v_lshl_add_u64 v[222:223], v[158:159], 0, s[4:5]
	s_mov_b32 m0, s19
	v_readfirstlane_b32 s19, v224
	v_add_u32_e32 v224, s17, v140
	global_load_lds_dwordx4 v[222:223], off
	v_lshl_add_u64 v[222:223], v[150:151], 0, s[4:5]
	s_mov_b32 m0, s19
	v_readfirstlane_b32 s19, v224
	v_add_u32_e32 v224, s18, v140
	global_load_lds_dwordx4 v[222:223], off
	v_lshl_add_u64 v[222:223], v[156:157], 0, s[4:5]
	s_mov_b32 m0, s19
	v_readfirstlane_b32 s19, v224
	v_add_u32_e32 v224, s17, v142
	global_load_lds_dwordx4 v[222:223], off
	v_lshl_add_u64 v[222:223], v[148:149], 0, s[4:5]
	s_mov_b32 m0, s19
	v_readfirstlane_b32 s17, v224
	v_add_u32_e32 v224, s18, v142
	global_load_lds_dwordx4 v[222:223], off
	v_lshl_add_u64 v[222:223], v[154:155], 0, s[4:5]
	s_mov_b32 m0, s17
	v_readfirstlane_b32 s17, v224
	global_load_lds_dwordx4 v[222:223], off
	v_lshl_add_u64 v[222:223], v[146:147], 0, s[4:5]
	s_mov_b32 m0, s17
	s_nop 0
	global_load_lds_dwordx4 v[222:223], off
	s_waitcnt vmcnt(8) lgkmcnt(0)
	s_barrier
	s_branch .LBB0_262

; #define MFMA16(a, b, c) __builtin_amdgcn_mfma_f32_16x16x32_bf16((a), (b), (c), 0, 0, 0)
;   DI unsigned koff(int k) const { return (unsigned)((k >> 6) * EIN + (k & 63)); }
; DI void dma16(const void* g, unsigned char* l) { __builtin_amdgcn_global_load_lds((const unsigned*)g, (lds_u32_t*)(unsigned)(size_t)l, 16, 0, 0); }
; template <class AF, class EF>
; DI void gemm_run(unsigned char* lds, int wv, const AF& af, const bf16_t* __restrict__ Bt, int ldb, int M, int N, int K, const EF& ef, int blk_off) {
;     ...
;       if (kt + 1 < nk) {
;         unsigned char* nxt = sBase + ((kt + 1) & 1) * GST;
;         const int k0 = (kt + 1) << 6;
; #pragma unroll
;         for (int i = 0; i < 4; ++i) {
;           dma16(Ab + aoff[i] + af.koff(k0 + cch), nxt + 32768 + (i * 512 + tid) * 16);
;           dma16(Bt + boff[i] + (unsigned)k0, nxt + (i * 512 + tid) * 16);
;         }
;       }
; #pragma unroll
;       for (int ks = 0; ks < 2; ++ks) {
;         bf16x8 wf[4], xf[8];
; #pragma unroll
;         for (int i = 0; i < 4; ++i) wf[i] = *(const bf16x8*)(cur + (wn * 64 + i * 16 + l15) * 128 + (((ks * 4 + q4) ^ swz) * 16));
; #pragma unroll
;         for (int j = 0; j < 8; ++j) xf[j] = *(const bf16x8*)(cur + 32768 + (wm * 128 + j * 16 + l15) * 128 + (((ks * 4 + q4) ^ swz) * 16));
; #pragma unroll
;         for (int i = 0; i < 4; ++i)
; #pragma unroll
;           for (int j = 0; j < 8; ++j) acc[i][j] = MFMA16(wf[i], xf[j], acc[i][j]);
;       }
.Lmyg261_loop:
	s_waitcnt lgkmcnt(7)
	v_mfma_f32_16x16x32_bf16 v[126:129], v[130:133], v[180:183], v[126:129]
	ds_read_b128 v[226:229], v212 offset:10240
	s_waitcnt lgkmcnt(7)
	v_mfma_f32_16x16x32_bf16 v[118:121], v[130:133], v[184:187], v[118:121]
	s_waitcnt lgkmcnt(6)
	v_mfma_f32_16x16x32_bf16 v[110:113], v[130:133], v[188:191], v[110:113]
	s_waitcnt lgkmcnt(5)
	v_mfma_f32_16x16x32_bf16 v[102:105], v[130:133], v[192:195], v[102:105]
	s_waitcnt lgkmcnt(4)
	v_mfma_f32_16x16x32_bf16 v[94:97], v[130:133], v[196:199], v[94:97]
	s_waitcnt lgkmcnt(3)
	v_mfma_f32_16x16x32_bf16 v[86:89], v[130:133], v[200:203], v[86:89]
	s_waitcnt lgkmcnt(2)
	v_mfma_f32_16x16x32_bf16 v[78:81], v[130:133], v[204:207], v[78:81]
	s_waitcnt lgkmcnt(1)
	v_mfma_f32_16x16x32_bf16 v[70:73], v[130:133], v[208:211], v[70:73]
	s_waitcnt lgkmcnt(0)
	v_mfma_f32_16x16x32_bf16 v[122:125], v[226:229], v[180:183], v[122:125]
	ds_read_b128 v[130:133], v212 offset:12288
	v_mfma_f32_16x16x32_bf16 v[114:117], v[226:229], v[184:187], v[114:117]
	v_mfma_f32_16x16x32_bf16 v[106:109], v[226:229], v[188:191], v[106:109]
	v_mfma_f32_16x16x32_bf16 v[98:101], v[226:229], v[192:195], v[98:101]
	v_mfma_f32_16x16x32_bf16 v[90:93], v[226:229], v[196:199], v[90:93]
	v_mfma_f32_16x16x32_bf16 v[82:85], v[226:229], v[200:203], v[82:85]
	v_mfma_f32_16x16x32_bf16 v[74:77], v[226:229], v[204:207], v[74:77]
	v_mfma_f32_16x16x32_bf16 v[66:69], v[226:229], v[208:211], v[66:69]
	s_bitcmp1_b32 s101, 0
	s_cbranch_scc0 .Lmyg261_noB
	s_andn2_b32 s101, s101, 1
	s_setprio 3
	s_and_b32 s17, s16, 0x10000
	s_add_i32 s17, s17, 0
	s_add_i32 s18, s17, 0x2000
	s_add_i32 s17, s17, 0xa000
	v_add_u32_e32 v224, s17, v136
	v_lshl_add_u64 v[222:223], v[160:161], 0, s[4:5]
	v_readfirstlane_b32 s19, v224
	v_add_u32_e32 v224, s18, v136
	s_mov_b32 m0, s19
	v_readfirstlane_b32 s19, v224
	v_add_u32_e32 v224, s17, v138
	global_load_lds_dwordx4 v[222:223], off
	v_lshl_add_u64 v[222:223], v[152:153], 0, s[4:5]
	s_mov_b32 m0, s19
	v_readfirstlane_b32 s19, v224
	v_add_u32_e32 v224, s18, v138
	global_load_lds_dwordx4 v[222:223], off
	v_lshl_add_u64 v[222:223], v[158:159], 0, s[4:5]
	s_mov_b32 m0, s19
	v_readfirstlane_b32 s19, v224
	v_add_u32_e32 v224, s17, v140
	global_load_lds_dwordx4 v[222:223], off
	v_lshl_add_u64 v[222:223], v[150:151], 0, s[4:5]
	s_mov_b32 m0, s19
	v_readfirstlane_b32 s19, v224
	v_add_u32_e32 v224, s18, v140
	global_load_lds_dwordx4 v[222:223], off
	v_lshl_add_u64 v[222:223], v[156:157], 0, s[4:5]
	s_mov_b32 m0, s19
	v_readfirstlane_b32 s19, v224
	v_add_u32_e32 v224, s17, v142
	global_load_lds_dwordx4 v[222:223], off
	v_lshl_add_u64 v[222:223], v[148:149], 0, s[4:5]
	s_mov_b32 m0, s19
	v_readfirstlane_b32 s17, v224
	v_add_u32_e32 v224, s18, v142
	global_load_lds_dwordx4 v[222:223], off
	v_lshl_add_u64 v[222:223], v[154:155], 0, s[4:5]
	s_mov_b32 m0, s17
	v_readfirstlane_b32 s17, v224
	global_load_lds_dwordx4 v[222:223], off
	v_lshl_add_u64 v[222:223], v[146:147], 0, s[4:5]
	s_mov_b32 m0, s17
	s_nop 0
	global_load_lds_dwordx4 v[222:223], off
	s_setprio 0
; #define MFMA16(a, b, c) __builtin_amdgcn_mfma_f32_16x16x32_bf16((a), (b), (c), 0, 0, 0)
; DI void vm_wait0() { asm volatile("s_waitcnt vmcnt(0)" ::: "memory"); }
;   DI unsigned koff(int k) const { return (unsigned)((k >> 6) * EIN + (k & 63)); }
; DI void dma16(const void* g, unsigned char* l) { __builtin_amdgcn_global_load_lds((const unsigned*)g, (lds_u32_t*)(unsigned)(size_t)l, 16, 0, 0); }
; template <class AF, class EF>
; DI void gemm_run(unsigned char* lds, int wv, const AF& af, const bf16_t* __restrict__ Bt, int ldb, int M, int N, int K, const EF& ef, int blk_off) {
;     ...
;       if (kt + 1 < nk) {
;         unsigned char* nxt = sBase + ((kt + 1) & 1) * GST;
;         const int k0 = (kt + 1) << 6;
; #pragma unroll
;         for (int i = 0; i < 4; ++i) {
;           dma16(Ab + aoff[i] + af.koff(k0 + cch), nxt + 32768 + (i * 512 + tid) * 16);
;           dma16(Bt + boff[i] + (unsigned)k0, nxt + (i * 512 + tid) * 16);
;         }
;     ...
; #pragma unroll
;       for (int ks = 0; ks < 2; ++ks) {
;         bf16x8 wf[4], xf[8];
; #pragma unroll
;         for (int i = 0; i < 4; ++i) wf[i] = *(const bf16x8*)(cur + (wn * 64 + i * 16 + l15) * 128 + (((ks * 4 + q4) ^ swz) * 16));
; #pragma unroll
;         for (int j = 0; j < 8; ++j) xf[j] = *(const bf16x8*)(cur + 32768 + (wm * 128 + j * 16 + l15) * 128 + (((ks * 4 + q4) ^ swz) * 16));
; #pragma unroll
;         for (int i = 0; i < 4; ++i)
; #pragma unroll
;           for (int j = 0; j < 8; ++j) acc[i][j] = MFMA16(wf[i], xf[j], acc[i][j]);
;       }
;       vm_wait0();
;       __syncthreads();
;     }
.Lmyg261_noB:
	s_waitcnt lgkmcnt(0)
	v_mfma_f32_16x16x32_bf16 v[62:65], v[130:133], v[180:183], v[62:65]
	ds_read_b128 v[226:229], v212 offset:14336
	v_mfma_f32_16x16x32_bf16 v[54:57], v[130:133], v[184:187], v[54:57]
	v_add_u32_e32 v0, s100, v179
	v_mfma_f32_16x16x32_bf16 v[46:49], v[130:133], v[188:191], v[46:49]
	v_add3_u32 v212, v0, v176, v177
	v_mfma_f32_16x16x32_bf16 v[38:41], v[130:133], v[192:195], v[38:41]
	v_add3_u32 v0, v0, v178, v177
	v_mfma_f32_16x16x32_bf16 v[30:33], v[130:133], v[196:199], v[30:33]
	v_mfma_f32_16x16x32_bf16 v[22:25], v[130:133], v[200:203], v[22:25]
	v_mfma_f32_16x16x32_bf16 v[14:17], v[130:133], v[204:207], v[14:17]
	v_mfma_f32_16x16x32_bf16 v[2:5], v[130:133], v[208:211], v[2:5]
	s_waitcnt lgkmcnt(0)
	v_mfma_f32_16x16x32_bf16 v[58:61], v[226:229], v[180:183], v[58:61]
	ds_read_b128 v[130:133], v212 offset:8192
	ds_read_b128 v[180:183], v0 offset:40960
	v_mfma_f32_16x16x32_bf16 v[50:53], v[226:229], v[184:187], v[50:53]
	ds_read_b128 v[184:187], v0 offset:43008
	v_mfma_f32_16x16x32_bf16 v[42:45], v[226:229], v[188:191], v[42:45]
	ds_read_b128 v[188:191], v0 offset:45056
	v_mfma_f32_16x16x32_bf16 v[34:37], v[226:229], v[192:195], v[34:37]
	ds_read_b128 v[192:195], v0 offset:47104
	v_mfma_f32_16x16x32_bf16 v[26:29], v[226:229], v[196:199], v[26:29]
	ds_read_b128 v[196:199], v0 offset:49152
	v_mfma_f32_16x16x32_bf16 v[18:21], v[226:229], v[200:203], v[18:21]
	ds_read_b128 v[200:203], v0 offset:51200
	v_mfma_f32_16x16x32_bf16 v[10:13], v[226:229], v[204:207], v[10:13]
	ds_read_b128 v[204:207], v0 offset:53248
	v_mfma_f32_16x16x32_bf16 v[6:9], v[226:229], v[208:211], v[6:9]
	ds_read_b128 v[208:211], v0 offset:55296
	s_waitcnt lgkmcnt(7)
	v_mfma_f32_16x16x32_bf16 v[126:129], v[130:133], v[180:183], v[126:129]
	ds_read_b128 v[226:229], v212 offset:10240
	s_waitcnt lgkmcnt(7)
	v_mfma_f32_16x16x32_bf16 v[118:121], v[130:133], v[184:187], v[118:121]
	s_waitcnt lgkmcnt(6)
	v_mfma_f32_16x16x32_bf16 v[110:113], v[130:133], v[188:191], v[110:113]
	s_waitcnt lgkmcnt(5)
	v_mfma_f32_16x16x32_bf16 v[102:105], v[130:133], v[192:195], v[102:105]
	s_waitcnt lgkmcnt(4)
	v_mfma_f32_16x16x32_bf16 v[94:97], v[130:133], v[196:199], v[94:97]
	s_waitcnt lgkmcnt(3)
	v_mfma_f32_16x16x32_bf16 v[86:89], v[130:133], v[200:203], v[86:89]
	s_waitcnt lgkmcnt(2)
	v_mfma_f32_16x16x32_bf16 v[78:81], v[130:133], v[204:207], v[78:81]
	s_waitcnt lgkmcnt(1)
	v_mfma_f32_16x16x32_bf16 v[70:73], v[130:133], v[208:211], v[70:73]
	s_waitcnt lgkmcnt(0)
	v_mfma_f32_16x16x32_bf16 v[122:125], v[226:229], v[180:183], v[122:125]
	ds_read_b128 v[130:133], v212 offset:12288
	v_mfma_f32_16x16x32_bf16 v[114:117], v[226:229], v[184:187], v[114:117]
	v_mfma_f32_16x16x32_bf16 v[106:109], v[226:229], v[188:191], v[106:109]
	v_mfma_f32_16x16x32_bf16 v[98:101], v[226:229], v[192:195], v[98:101]
	v_mfma_f32_16x16x32_bf16 v[90:93], v[226:229], v[196:199], v[90:93]
	v_mfma_f32_16x16x32_bf16 v[82:85], v[226:229], v[200:203], v[82:85]
	v_mfma_f32_16x16x32_bf16 v[74:77], v[226:229], v[204:207], v[74:77]
	v_mfma_f32_16x16x32_bf16 v[66:69], v[226:229], v[208:211], v[66:69]
	s_waitcnt lgkmcnt(0)
	v_mfma_f32_16x16x32_bf16 v[62:65], v[130:133], v[180:183], v[62:65]
	ds_read_b128 v[226:229], v212 offset:14336
	v_mfma_f32_16x16x32_bf16 v[54:57], v[130:133], v[184:187], v[54:57]
	v_mfma_f32_16x16x32_bf16 v[46:49], v[130:133], v[188:191], v[46:49]
	v_mfma_f32_16x16x32_bf16 v[38:41], v[130:133], v[192:195], v[38:41]
	v_mfma_f32_16x16x32_bf16 v[30:33], v[130:133], v[196:199], v[30:33]
	v_mfma_f32_16x16x32_bf16 v[22:25], v[130:133], v[200:203], v[22:25]
	v_mfma_f32_16x16x32_bf16 v[14:17], v[130:133], v[204:207], v[14:17]
	v_mfma_f32_16x16x32_bf16 v[2:5], v[130:133], v[208:211], v[2:5]
	s_waitcnt vmcnt(0) lgkmcnt(0)
	s_barrier
	s_add_u32 s4, s4, 0x80
	s_addc_u32 s5, s5, 0
	s_add_i32 s16, s16, 0x10000
	s_cmpk_eq_i32 s4, 0x800
	s_cbranch_scc1 .Lmyg261_tail
	s_add_i32 s100, s16, 0xffff0000
	s_and_b32 s100, s100, 0x10000
	v_add_u32_e32 v0, s100, v175
	v_add3_u32 v212, v0, v176, v177
	v_add3_u32 v0, v0, v178, v177
	s_cmpk_eq_i32 s4, 0x780
	s_cbranch_scc1 .Lmyg261_nodma
	s_bitcmp1_b32 s101, 1
	s_cbranch_scc1 .Lmyg261_defer
	s_setprio 3
	s_and_b32 s17, s16, 0x10000
	s_add_i32 s17, s17, 0
	s_add_i32 s18, s17, 0x2000
	s_add_i32 s17, s17, 0xa000
	v_add_u32_e32 v224, s17, v136
	v_lshl_add_u64 v[222:223], v[160:161], 0, s[4:5]
	v_readfirstlane_b32 s19, v224
	v_add_u32_e32 v224, s18, v136
	s_mov_b32 m0, s19
	v_readfirstlane_b32 s19, v224
	v_add_u32_e32 v224, s17, v138
	global_load_lds_dwordx4 v[222:223], off
	v_lshl_add_u64 v[222:223], v[152:153], 0, s[4:5]
	s_mov_b32 m0, s19
	v_readfirstlane_b32 s19, v224
	v_add_u32_e32 v224, s18, v138
	global_load_lds_dwordx4 v[222:223], off
	v_lshl_add_u64 v[222:223], v[158:159], 0, s[4:5]
	s_mov_b32 m0, s19
	v_readfirstlane_b32 s19, v224
	v_add_u32_e32 v224, s17, v140
	global_load_lds_dwordx4 v[222:223], off
	v_lshl_add_u64 v[222:223], v[150:151], 0, s[4:5]
	s_mov_b32 m0, s19
	v_readfirstlane_b32 s19, v224
	v_add_u32_e32 v224, s18, v140
	global_load_lds_dwordx4 v[222:223], off
	v_lshl_add_u64 v[222:223], v[156:157], 0, s[4:5]
	s_mov_b32 m0, s19
	v_readfirstlane_b32 s19, v224
	v_add_u32_e32 v224, s17, v142
	global_load_lds_dwordx4 v[222:223], off
	v_lshl_add_u64 v[222:223], v[148:149], 0, s[4:5]
	s_mov_b32 m0, s19
	v_readfirstlane_b32 s17, v224
	v_add_u32_e32 v224, s18, v142
	global_load_lds_dwordx4 v[222:223], off
	v_lshl_add_u64 v[222:223], v[154:155], 0, s[4:5]
	s_mov_b32 m0, s17
	v_readfirstlane_b32 s17, v224
	global_load_lds_dwordx4 v[222:223], off
	v_lshl_add_u64 v[222:223], v[146:147], 0, s[4:5]
	s_mov_b32 m0, s17
	s_nop 0
	global_load_lds_dwordx4 v[222:223], off
	s_setprio 0
	s_branch .Lmyg261_nodma

;   DI unsigned rowoff(int m) const { int combo = m >> 9, n = m & 511, b = combo >> 1, g = combo & 1; return (unsigned)((b * SEQ + 16 * n) * EIN + col0 + g * 64); }
;   DI unsigned koff(int k) const { return (unsigned)((k >> 6) * EIN + (k & 63)); }
; DI void dma16(const void* g, unsigned char* l) { __builtin_amdgcn_global_load_lds((const unsigned*)g, (lds_u32_t*)(unsigned)(size_t)l, 16, 0, 0); }
; template <class AF, class EF>
; DI void gemm_run(unsigned char* lds, int wv, const AF& af, const bf16_t* __restrict__ Bt, int ldb, int M, int N, int K, const EF& ef, int blk_off) {
;     ...
;   for (int tile_ = first; tile_ < ntl_eff; tile_ += tstep) {
;     int nt, mt;
;     if (xmap) { nt = tile_ % ntiles; mt = (tile_ / ntiles) * 8 + ((int)blockIdx.x & 7); }
;     else { nt = tile_ % ntiles; mt = tile_ / ntiles; }
;     const int m0 = mt << 8, n0 = nt << 8;
;     f32x4 acc[4][8];
; #pragma unroll
;     for (int i = 0; i < 4; ++i)
; #pragma unroll
;       for (int j = 0; j < 8; ++j) acc[i][j] = (f32x4){0.f, 0.f, 0.f, 0.f};
;     unsigned aoff[4], boff[4];
;     const bf16_t* Ab = af.base();
; #pragma unroll
;     for (int i = 0; i < 4; ++i) {
;       int row = crow + 64 * i;
;       aoff[i] = af.rowoff(m0 + row);
;       int n = n0 + row; n = n < N ? n : N - 1;
;       boff[i] = (unsigned)(n * ldb + cch);
;     }
;     __syncthreads();
; #pragma unroll
;     for (int i = 0; i < 4; ++i) {
;       dma16(Ab + aoff[i] + af.koff(cch), sBase + 32768 + (i * 512 + tid) * 16);
;       dma16(Bt + boff[i], sBase + (i * 512 + tid) * 16);
;     }
.LBB0_1244:
	s_ashr_i32 s14, s16, 31
	s_lshr_b32 s14, s14, 30
	s_add_i32 s18, s16, s14
	s_ashr_i32 s17, s18, 2
	s_lshl_b32 s14, s17, 3
	s_or_b32 s19, s14, s78
	v_readlane_b32 s14, v254, 34
	v_readlane_b32 s15, v254, 35
	s_and_b64 s[14:15], s[14:15], exec
	s_cselect_b32 s14, s19, s17
	s_lshl_b32 s17, s14, 8
	s_and_b32 s14, s18, 0xfffffc
	s_sub_i32 s14, s16, s14
	s_lshl_b32 s18, s14, 8
	v_add_u32_e32 v3, s18, v168
	v_min_i32_e32 v3, 0x3ff, v3
	v_lshl_or_b32 v6, v3, 10, v145
	v_add_u32_e32 v3, s18, v169
	v_min_i32_e32 v3, 0x3ff, v3
	v_add_u32_e32 v2, s18, v143
	v_lshl_or_b32 v10, v3, 10, v145
	v_add_u32_e32 v3, s18, v170
	v_add_lshl_u32 v0, s17, v143, 10
	v_min_i32_e32 v2, 0x3ff, v2
	v_min_i32_e32 v3, 0x3ff, v3
	v_lshl_or_b32 v2, v2, 10, v145
	v_lshl_or_b32 v14, v3, 10, v145
	v_lshlrev_b64 v[16:17], 1, v[0:1]
	v_readfirstlane_b32 s14, v171
	v_mov_b32_e32 v3, v1
	v_add_lshl_u32 v4, s17, v168, 10
	v_lshl_add_u64 v[18:19], v[138:139], 0, v[16:17]
	s_mov_b32 m0, s14
	v_lshlrev_b64 v[2:3], 1, v[2:3]
	v_readfirstlane_b32 s14, v172
	v_mov_b32_e32 v5, v1
	s_waitcnt lgkmcnt(0)
	s_barrier
; DI void vm_wait0() { asm volatile("s_waitcnt vmcnt(0)" ::: "memory"); }
;   DI unsigned rowoff(int m) const { int combo = m >> 9, n = m & 511, b = combo >> 1, g = combo & 1; return (unsigned)((b * SEQ + 16 * n) * EIN + col0 + g * 64); }
;   DI unsigned koff(int k) const { return (unsigned)((k >> 6) * EIN + (k & 63)); }
; DI void dma16(const void* g, unsigned char* l) { __builtin_amdgcn_global_load_lds((const unsigned*)g, (lds_u32_t*)(unsigned)(size_t)l, 16, 0, 0); }
; template <class AF, class EF>
; DI void gemm_run(unsigned char* lds, int wv, const AF& af, const bf16_t* __restrict__ Bt, int ldb, int M, int N, int K, const EF& ef, int blk_off) {
;     ...
;     f32x4 acc[4][8];
; #pragma unroll
;     for (int i = 0; i < 4; ++i)
; #pragma unroll
;       for (int j = 0; j < 8; ++j) acc[i][j] = (f32x4){0.f, 0.f, 0.f, 0.f};
;     unsigned aoff[4], boff[4];
;     const bf16_t* Ab = af.base();
; #pragma unroll
;     for (int i = 0; i < 4; ++i) {
;       int row = crow + 64 * i;
;       aoff[i] = af.rowoff(m0 + row);
;       int n = n0 + row; n = n < N ? n : N - 1;
;       boff[i] = (unsigned)(n * ldb + cch);
;     }
;     __syncthreads();
; #pragma unroll
;     for (int i = 0; i < 4; ++i) {
;       dma16(Ab + aoff[i] + af.koff(cch), sBase + 32768 + (i * 512 + tid) * 16);
;       dma16(Bt + boff[i], sBase + (i * 512 + tid) * 16);
;     }
;     vm_wait0();
;     __syncthreads();
; #pragma unroll 1
;     for (int kt = 0; kt < nk; ++kt) {
;       unsigned char* cur = sBase + (kt & 1) * GST;
;       if (kt + 1 < nk) {
;         unsigned char* nxt = sBase + ((kt + 1) & 1) * GST;
;         const int k0 = (kt + 1) << 6;
; #pragma unroll
;         for (int i = 0; i < 4; ++i) {
;           dma16(Ab + aoff[i] + af.koff(k0 + cch), nxt + 32768 + (i * 512 + tid) * 16);
;           dma16(Bt + boff[i] + (unsigned)k0, nxt + (i * 512 + tid) * 16);
;         }
	global_load_lds_dwordx4 v[18:19], off
	v_lshl_add_u64 v[18:19], s[4:5], 0, v[2:3]
	s_mov_b32 m0, s14
	v_lshlrev_b64 v[4:5], 1, v[4:5]
	v_readfirstlane_b32 s14, v173
	v_mov_b32_e32 v7, v1
	v_add_lshl_u32 v8, s17, v169, 10
	global_load_lds_dwordx4 v[18:19], off
	v_lshl_add_u64 v[18:19], v[138:139], 0, v[4:5]
	s_mov_b32 m0, s14
	v_lshlrev_b64 v[6:7], 1, v[6:7]
	v_readfirstlane_b32 s14, v174
	v_mov_b32_e32 v9, v1
	global_load_lds_dwordx4 v[18:19], off
	v_lshl_add_u64 v[18:19], s[4:5], 0, v[6:7]
	s_mov_b32 m0, s14
	v_lshlrev_b64 v[8:9], 1, v[8:9]
	v_readfirstlane_b32 s14, v175
	v_mov_b32_e32 v11, v1
	v_add_lshl_u32 v12, s17, v170, 10
	global_load_lds_dwordx4 v[18:19], off
	v_lshl_add_u64 v[18:19], v[138:139], 0, v[8:9]
	s_mov_b32 m0, s14
	v_lshlrev_b64 v[10:11], 1, v[10:11]
	v_readfirstlane_b32 s14, v176
	v_mov_b32_e32 v13, v1
	global_load_lds_dwordx4 v[18:19], off
	v_lshl_add_u64 v[18:19], s[4:5], 0, v[10:11]
	s_mov_b32 m0, s14
	v_lshlrev_b64 v[12:13], 1, v[12:13]
	v_readfirstlane_b32 s14, v177
	v_mov_b32_e32 v15, v1
	global_load_lds_dwordx4 v[18:19], off
	v_lshl_add_u64 v[18:19], v[138:139], 0, v[12:13]
	s_mov_b32 m0, s14
	v_lshlrev_b64 v[14:15], 1, v[14:15]
	v_readfirstlane_b32 s14, v178
	global_load_lds_dwordx4 v[18:19], off
	v_lshl_add_u64 v[18:19], s[4:5], 0, v[14:15]
	s_mov_b32 m0, s14
	v_lshl_add_u64 v[156:157], s[12:13], 0, v[2:3]
	global_load_lds_dwordx4 v[18:19], off
	v_mov_b32_e32 v2, 0
	v_lshl_add_u64 v[150:151], s[12:13], 0, v[14:15]
	v_lshl_add_u64 v[152:153], s[12:13], 0, v[10:11]
	v_lshl_add_u64 v[154:155], s[12:13], 0, v[6:7]
	v_lshl_add_u64 v[158:159], v[148:149], 0, v[12:13]
	v_lshl_add_u64 v[160:161], v[148:149], 0, v[8:9]
	v_lshl_add_u64 v[164:165], v[148:149], 0, v[4:5]
	v_lshl_add_u64 v[166:167], v[148:149], 0, v[16:17]
	s_mov_b32 s19, 0
	s_mov_b64 s[14:15], 0
	s_mov_b32 s20, 0x10000
	v_mov_b32_e32 v3, v2
	v_mov_b32_e32 v4, v2
	v_mov_b32_e32 v5, v2
	v_mov_b32_e32 v6, v2
	v_mov_b32_e32 v7, v2
	v_mov_b32_e32 v8, v2
	v_mov_b32_e32 v9, v2
	v_mov_b32_e32 v10, v2
	v_mov_b32_e32 v11, v2
	v_mov_b32_e32 v12, v2
	v_mov_b32_e32 v13, v2
	v_mov_b32_e32 v14, v2
	v_mov_b32_e32 v15, v2
	v_mov_b32_e32 v16, v2
	v_mov_b32_e32 v17, v2
	v_mov_b32_e32 v30, v2
	v_mov_b32_e32 v31, v2
	v_mov_b32_e32 v32, v2
	v_mov_b32_e32 v33, v2
	v_mov_b32_e32 v42, v2
	v_mov_b32_e32 v43, v2
	v_mov_b32_e32 v44, v2
	v_mov_b32_e32 v45, v2
	v_mov_b32_e32 v50, v2
	v_mov_b32_e32 v51, v2
	v_mov_b32_e32 v52, v2
	v_mov_b32_e32 v53, v2
	v_mov_b32_e32 v58, v2
	v_mov_b32_e32 v59, v2
	v_mov_b32_e32 v60, v2
	v_mov_b32_e32 v61, v2
	v_mov_b32_e32 v66, v2
	v_mov_b32_e32 v67, v2
	v_mov_b32_e32 v68, v2
	v_mov_b32_e32 v69, v2
	v_mov_b32_e32 v74, v2
	v_mov_b32_e32 v75, v2
	v_mov_b32_e32 v76, v2
	v_mov_b32_e32 v77, v2
	v_mov_b32_e32 v82, v2
	v_mov_b32_e32 v83, v2
	v_mov_b32_e32 v84, v2
	v_mov_b32_e32 v85, v2
	v_mov_b32_e32 v90, v2
	v_mov_b32_e32 v91, v2
	v_mov_b32_e32 v92, v2
	v_mov_b32_e32 v93, v2
	v_mov_b32_e32 v98, v2
	v_mov_b32_e32 v99, v2
	v_mov_b32_e32 v100, v2
	v_mov_b32_e32 v101, v2
	v_mov_b32_e32 v106, v2
	v_mov_b32_e32 v107, v2
	v_mov_b32_e32 v108, v2
	v_mov_b32_e32 v109, v2
	v_mov_b32_e32 v114, v2
	v_mov_b32_e32 v115, v2
	v_mov_b32_e32 v116, v2
	v_mov_b32_e32 v117, v2
	v_mov_b32_e32 v122, v2
	v_mov_b32_e32 v123, v2
	v_mov_b32_e32 v124, v2
	v_mov_b32_e32 v125, v2
	v_mov_b32_e32 v70, v2
	v_mov_b32_e32 v71, v2
	v_mov_b32_e32 v72, v2
	v_mov_b32_e32 v73, v2
	v_mov_b32_e32 v78, v2
	v_mov_b32_e32 v79, v2
	v_mov_b32_e32 v80, v2
	v_mov_b32_e32 v81, v2
	v_mov_b32_e32 v86, v2
	v_mov_b32_e32 v87, v2
	v_mov_b32_e32 v88, v2
	v_mov_b32_e32 v89, v2
	v_mov_b32_e32 v94, v2
	v_mov_b32_e32 v95, v2
	v_mov_b32_e32 v96, v2
	v_mov_b32_e32 v97, v2
	v_mov_b32_e32 v102, v2
	v_mov_b32_e32 v103, v2
	v_mov_b32_e32 v104, v2
	v_mov_b32_e32 v105, v2
	v_mov_b32_e32 v110, v2
	v_mov_b32_e32 v111, v2
	v_mov_b32_e32 v112, v2
	v_mov_b32_e32 v113, v2
	v_mov_b32_e32 v118, v2
	v_mov_b32_e32 v119, v2
	v_mov_b32_e32 v120, v2
	v_mov_b32_e32 v121, v2
	v_mov_b32_e32 v126, v2
	v_mov_b32_e32 v127, v2
	v_mov_b32_e32 v128, v2
	v_mov_b32_e32 v129, v2
	v_mov_b32_e32 v62, v2
	v_mov_b32_e32 v63, v2
	v_mov_b32_e32 v64, v2
	v_mov_b32_e32 v65, v2
	v_mov_b32_e32 v54, v2
	v_mov_b32_e32 v55, v2
	v_mov_b32_e32 v56, v2
	v_mov_b32_e32 v57, v2
	v_mov_b32_e32 v46, v2
	v_mov_b32_e32 v47, v2
	v_mov_b32_e32 v48, v2
	v_mov_b32_e32 v49, v2
	v_mov_b32_e32 v38, v2
	v_mov_b32_e32 v39, v2
	v_mov_b32_e32 v40, v2
	v_mov_b32_e32 v41, v2
	v_mov_b32_e32 v26, v2
	v_mov_b32_e32 v27, v2
	v_mov_b32_e32 v28, v2
	v_mov_b32_e32 v29, v2
	v_mov_b32_e32 v22, v2
	v_mov_b32_e32 v23, v2
	v_mov_b32_e32 v24, v2
	v_mov_b32_e32 v25, v2
	v_mov_b32_e32 v34, v2
	v_mov_b32_e32 v35, v2
	v_mov_b32_e32 v36, v2
	v_mov_b32_e32 v37, v2
	v_mov_b32_e32 v18, v2
	v_mov_b32_e32 v19, v2
	v_mov_b32_e32 v20, v2
	v_mov_b32_e32 v21, v2
	v_readlane_b32 s101, v254, 0
	s_nop 3
	s_lshr_b32 s101, s101, 8
	s_lshl_b32 s101, s101, 1
	s_and_b32 s21, s20, 0x10000
	s_add_i32 s21, s21, 0
	s_add_i32 s22, s21, 0x2000
	s_add_i32 s21, s21, 0xa000
	v_add_u32_e32 v224, s21, v140
	v_lshl_add_u64 v[222:223], v[166:167], 0, s[14:15]
	v_readfirstlane_b32 s23, v224
	v_add_u32_e32 v224, s22, v140
	s_mov_b32 m0, s23
	v_readfirstlane_b32 s23, v224
	v_add_u32_e32 v224, s21, v142
	global_load_lds_dwordx4 v[222:223], off
	v_lshl_add_u64 v[222:223], v[156:157], 0, s[14:15]
	s_mov_b32 m0, s23
	v_readfirstlane_b32 s23, v224
	v_add_u32_e32 v224, s22, v142
	global_load_lds_dwordx4 v[222:223], off
	v_lshl_add_u64 v[222:223], v[164:165], 0, s[14:15]
	s_mov_b32 m0, s23
	v_readfirstlane_b32 s23, v224
	v_add_u32_e32 v224, s21, v144
	global_load_lds_dwordx4 v[222:223], off
	v_lshl_add_u64 v[222:223], v[154:155], 0, s[14:15]
	s_mov_b32 m0, s23
	v_readfirstlane_b32 s23, v224
	v_add_u32_e32 v224, s22, v144
	global_load_lds_dwordx4 v[222:223], off
	v_lshl_add_u64 v[222:223], v[160:161], 0, s[14:15]
	s_mov_b32 m0, s23
	v_readfirstlane_b32 s23, v224
	v_add_u32_e32 v224, s21, v146
	global_load_lds_dwordx4 v[222:223], off
	v_lshl_add_u64 v[222:223], v[152:153], 0, s[14:15]
	s_mov_b32 m0, s23
	v_readfirstlane_b32 s21, v224
	v_add_u32_e32 v224, s22, v146
	global_load_lds_dwordx4 v[222:223], off
	v_lshl_add_u64 v[222:223], v[158:159], 0, s[14:15]
	s_mov_b32 m0, s21
	v_readfirstlane_b32 s21, v224
	global_load_lds_dwordx4 v[222:223], off
	v_lshl_add_u64 v[222:223], v[150:151], 0, s[14:15]
	s_mov_b32 m0, s21
	s_nop 0
	global_load_lds_dwordx4 v[222:223], off
	s_waitcnt vmcnt(8) lgkmcnt(0)
	s_barrier
	s_branch .LBB0_1246

; #define MFMA16(a, b, c) __builtin_amdgcn_mfma_f32_16x16x32_bf16((a), (b), (c), 0, 0, 0)
;   DI unsigned koff(int k) const { return (unsigned)((k >> 6) * EIN + (k & 63)); }
; DI void dma16(const void* g, unsigned char* l) { __builtin_amdgcn_global_load_lds((const unsigned*)g, (lds_u32_t*)(unsigned)(size_t)l, 16, 0, 0); }
; template <class AF, class EF>
; DI void gemm_run(unsigned char* lds, int wv, const AF& af, const bf16_t* __restrict__ Bt, int ldb, int M, int N, int K, const EF& ef, int blk_off) {
;     ...
;       if (kt + 1 < nk) {
;         unsigned char* nxt = sBase + ((kt + 1) & 1) * GST;
;         const int k0 = (kt + 1) << 6;
; #pragma unroll
;         for (int i = 0; i < 4; ++i) {
;           dma16(Ab + aoff[i] + af.koff(k0 + cch), nxt + 32768 + (i * 512 + tid) * 16);
;           dma16(Bt + boff[i] + (unsigned)k0, nxt + (i * 512 + tid) * 16);
;         }
;       }
; #pragma unroll
;       for (int ks = 0; ks < 2; ++ks) {
;         bf16x8 wf[4], xf[8];
; #pragma unroll
;         for (int i = 0; i < 4; ++i) wf[i] = *(const bf16x8*)(cur + (wn * 64 + i * 16 + l15) * 128 + (((ks * 4 + q4) ^ swz) * 16));
; #pragma unroll
;         for (int j = 0; j < 8; ++j) xf[j] = *(const bf16x8*)(cur + 32768 + (wm * 128 + j * 16 + l15) * 128 + (((ks * 4 + q4) ^ swz) * 16));
; #pragma unroll
;         for (int i = 0; i < 4; ++i)
; #pragma unroll
;           for (int j = 0; j < 8; ++j) acc[i][j] = MFMA16(wf[i], xf[j], acc[i][j]);
;       }
.Lmyg1245_loop:
	s_waitcnt lgkmcnt(7)
	v_mfma_f32_16x16x32_bf16 v[118:121], v[130:133], v[184:187], v[118:121]
	ds_read_b128 v[226:229], v212 offset:10240
	s_waitcnt lgkmcnt(7)
	v_mfma_f32_16x16x32_bf16 v[126:129], v[130:133], v[134:137], v[126:129]
	s_waitcnt lgkmcnt(6)
	v_mfma_f32_16x16x32_bf16 v[110:113], v[130:133], v[188:191], v[110:113]
	s_waitcnt lgkmcnt(5)
	v_mfma_f32_16x16x32_bf16 v[102:105], v[130:133], v[192:195], v[102:105]
	s_waitcnt lgkmcnt(4)
	v_mfma_f32_16x16x32_bf16 v[94:97], v[130:133], v[196:199], v[94:97]
	s_waitcnt lgkmcnt(3)
	v_mfma_f32_16x16x32_bf16 v[86:89], v[130:133], v[200:203], v[86:89]
	s_waitcnt lgkmcnt(2)
	v_mfma_f32_16x16x32_bf16 v[78:81], v[130:133], v[204:207], v[78:81]
	s_waitcnt lgkmcnt(1)
	v_mfma_f32_16x16x32_bf16 v[70:73], v[130:133], v[208:211], v[70:73]
	s_waitcnt lgkmcnt(0)
	v_mfma_f32_16x16x32_bf16 v[122:125], v[226:229], v[134:137], v[122:125]
	ds_read_b128 v[130:133], v212 offset:12288
	v_mfma_f32_16x16x32_bf16 v[114:117], v[226:229], v[184:187], v[114:117]
	v_mfma_f32_16x16x32_bf16 v[106:109], v[226:229], v[188:191], v[106:109]
	v_mfma_f32_16x16x32_bf16 v[98:101], v[226:229], v[192:195], v[98:101]
	v_mfma_f32_16x16x32_bf16 v[90:93], v[226:229], v[196:199], v[90:93]
	v_mfma_f32_16x16x32_bf16 v[82:85], v[226:229], v[200:203], v[82:85]
	v_mfma_f32_16x16x32_bf16 v[74:77], v[226:229], v[204:207], v[74:77]
	v_mfma_f32_16x16x32_bf16 v[66:69], v[226:229], v[208:211], v[66:69]
	s_bitcmp1_b32 s101, 0
	s_cbranch_scc0 .Lmyg1245_noB
	s_andn2_b32 s101, s101, 1
	s_setprio 3
	s_and_b32 s21, s20, 0x10000
	s_add_i32 s21, s21, 0
	s_add_i32 s22, s21, 0x2000
	s_add_i32 s21, s21, 0xa000
	v_add_u32_e32 v224, s21, v140
	v_lshl_add_u64 v[222:223], v[166:167], 0, s[14:15]
	v_readfirstlane_b32 s23, v224
	v_add_u32_e32 v224, s22, v140
	s_mov_b32 m0, s23
	v_readfirstlane_b32 s23, v224
	v_add_u32_e32 v224, s21, v142
	global_load_lds_dwordx4 v[222:223], off
	v_lshl_add_u64 v[222:223], v[156:157], 0, s[14:15]
	s_mov_b32 m0, s23
	v_readfirstlane_b32 s23, v224
	v_add_u32_e32 v224, s22, v142
	global_load_lds_dwordx4 v[222:223], off
	v_lshl_add_u64 v[222:223], v[164:165], 0, s[14:15]
	s_mov_b32 m0, s23
	v_readfirstlane_b32 s23, v224
	v_add_u32_e32 v224, s21, v144
	global_load_lds_dwordx4 v[222:223], off
	v_lshl_add_u64 v[222:223], v[154:155], 0, s[14:15]
	s_mov_b32 m0, s23
	v_readfirstlane_b32 s23, v224
	v_add_u32_e32 v224, s22, v144
	global_load_lds_dwordx4 v[222:223], off
	v_lshl_add_u64 v[222:223], v[160:161], 0, s[14:15]
	s_mov_b32 m0, s23
	v_readfirstlane_b32 s23, v224
	v_add_u32_e32 v224, s21, v146
	global_load_lds_dwordx4 v[222:223], off
	v_lshl_add_u64 v[222:223], v[152:153], 0, s[14:15]
	s_mov_b32 m0, s23
	v_readfirstlane_b32 s21, v224
	v_add_u32_e32 v224, s22, v146
	global_load_lds_dwordx4 v[222:223], off
	v_lshl_add_u64 v[222:223], v[158:159], 0, s[14:15]
	s_mov_b32 m0, s21
	v_readfirstlane_b32 s21, v224
	global_load_lds_dwordx4 v[222:223], off
	v_lshl_add_u64 v[222:223], v[150:151], 0, s[14:15]
	s_mov_b32 m0, s21
	s_nop 0
	global_load_lds_dwordx4 v[222:223], off
	s_setprio 0
; #define MFMA16(a, b, c) __builtin_amdgcn_mfma_f32_16x16x32_bf16((a), (b), (c), 0, 0, 0)
; DI void vm_wait0() { asm volatile("s_waitcnt vmcnt(0)" ::: "memory"); }
;   DI unsigned koff(int k) const { return (unsigned)((k >> 6) * EIN + (k & 63)); }
; DI void dma16(const void* g, unsigned char* l) { __builtin_amdgcn_global_load_lds((const unsigned*)g, (lds_u32_t*)(unsigned)(size_t)l, 16, 0, 0); }
; template <class AF, class EF>
; DI void gemm_run(unsigned char* lds, int wv, const AF& af, const bf16_t* __restrict__ Bt, int ldb, int M, int N, int K, const EF& ef, int blk_off) {
;     ...
;       if (kt + 1 < nk) {
;         unsigned char* nxt = sBase + ((kt + 1) & 1) * GST;
;         const int k0 = (kt + 1) << 6;
; #pragma unroll
;         for (int i = 0; i < 4; ++i) {
;           dma16(Ab + aoff[i] + af.koff(k0 + cch), nxt + 32768 + (i * 512 + tid) * 16);
;           dma16(Bt + boff[i] + (unsigned)k0, nxt + (i * 512 + tid) * 16);
;         }
;     ...
; #pragma unroll
;       for (int ks = 0; ks < 2; ++ks) {
;         bf16x8 wf[4], xf[8];
; #pragma unroll
;         for (int i = 0; i < 4; ++i) wf[i] = *(const bf16x8*)(cur + (wn * 64 + i * 16 + l15) * 128 + (((ks * 4 + q4) ^ swz) * 16));
; #pragma unroll
;         for (int j = 0; j < 8; ++j) xf[j] = *(const bf16x8*)(cur + 32768 + (wm * 128 + j * 16 + l15) * 128 + (((ks * 4 + q4) ^ swz) * 16));
; #pragma unroll
;         for (int i = 0; i < 4; ++i)
; #pragma unroll
;           for (int j = 0; j < 8; ++j) acc[i][j] = MFMA16(wf[i], xf[j], acc[i][j]);
;       }
;       vm_wait0();
;       __syncthreads();
;     }
.Lmyg1245_noB:
	s_waitcnt lgkmcnt(0)
	v_mfma_f32_16x16x32_bf16 v[58:61], v[130:133], v[134:137], v[58:61]
	ds_read_b128 v[226:229], v212 offset:14336
	v_mfma_f32_16x16x32_bf16 v[50:53], v[130:133], v[184:187], v[50:53]
	v_add_u32_e32 v0, s100, v183
	v_mfma_f32_16x16x32_bf16 v[42:45], v[130:133], v[188:191], v[42:45]
	v_add3_u32 v212, v0, v180, v181
	v_mfma_f32_16x16x32_bf16 v[30:33], v[130:133], v[192:195], v[30:33]
	v_add3_u32 v0, v0, v182, v181
	v_mfma_f32_16x16x32_bf16 v[14:17], v[130:133], v[196:199], v[14:17]
	v_mfma_f32_16x16x32_bf16 v[10:13], v[130:133], v[200:203], v[10:13]
	v_mfma_f32_16x16x32_bf16 v[6:9], v[130:133], v[204:207], v[6:9]
	v_mfma_f32_16x16x32_bf16 v[2:5], v[130:133], v[208:211], v[2:5]
	s_waitcnt lgkmcnt(0)
	v_mfma_f32_16x16x32_bf16 v[54:57], v[226:229], v[184:187], v[54:57]
	ds_read_b128 v[130:133], v212 offset:8192
	ds_read_b128 v[184:187], v0 offset:43008
	v_mfma_f32_16x16x32_bf16 v[62:65], v[226:229], v[134:137], v[62:65]
	ds_read_b128 v[134:137], v0 offset:40960
	v_mfma_f32_16x16x32_bf16 v[46:49], v[226:229], v[188:191], v[46:49]
	ds_read_b128 v[188:191], v0 offset:45056
	v_mfma_f32_16x16x32_bf16 v[38:41], v[226:229], v[192:195], v[38:41]
	ds_read_b128 v[192:195], v0 offset:47104
	v_mfma_f32_16x16x32_bf16 v[26:29], v[226:229], v[196:199], v[26:29]
	ds_read_b128 v[196:199], v0 offset:49152
	v_mfma_f32_16x16x32_bf16 v[22:25], v[226:229], v[200:203], v[22:25]
	ds_read_b128 v[200:203], v0 offset:51200
	v_mfma_f32_16x16x32_bf16 v[34:37], v[226:229], v[204:207], v[34:37]
	ds_read_b128 v[204:207], v0 offset:53248
	v_mfma_f32_16x16x32_bf16 v[18:21], v[226:229], v[208:211], v[18:21]
	ds_read_b128 v[208:211], v0 offset:55296
	s_waitcnt lgkmcnt(7)
	v_mfma_f32_16x16x32_bf16 v[118:121], v[130:133], v[184:187], v[118:121]
	ds_read_b128 v[226:229], v212 offset:10240
	s_waitcnt lgkmcnt(7)
	v_mfma_f32_16x16x32_bf16 v[126:129], v[130:133], v[134:137], v[126:129]
	s_waitcnt lgkmcnt(6)
	v_mfma_f32_16x16x32_bf16 v[110:113], v[130:133], v[188:191], v[110:113]
	s_waitcnt lgkmcnt(5)
	v_mfma_f32_16x16x32_bf16 v[102:105], v[130:133], v[192:195], v[102:105]
	s_waitcnt lgkmcnt(4)
	v_mfma_f32_16x16x32_bf16 v[94:97], v[130:133], v[196:199], v[94:97]
	s_waitcnt lgkmcnt(3)
	v_mfma_f32_16x16x32_bf16 v[86:89], v[130:133], v[200:203], v[86:89]
	s_waitcnt lgkmcnt(2)
	v_mfma_f32_16x16x32_bf16 v[78:81], v[130:133], v[204:207], v[78:81]
	s_waitcnt lgkmcnt(1)
	v_mfma_f32_16x16x32_bf16 v[70:73], v[130:133], v[208:211], v[70:73]
	s_waitcnt lgkmcnt(0)
	v_mfma_f32_16x16x32_bf16 v[122:125], v[226:229], v[134:137], v[122:125]
	ds_read_b128 v[130:133], v212 offset:12288
	v_mfma_f32_16x16x32_bf16 v[114:117], v[226:229], v[184:187], v[114:117]
	v_mfma_f32_16x16x32_bf16 v[106:109], v[226:229], v[188:191], v[106:109]
	v_mfma_f32_16x16x32_bf16 v[98:101], v[226:229], v[192:195], v[98:101]
	v_mfma_f32_16x16x32_bf16 v[90:93], v[226:229], v[196:199], v[90:93]
	v_mfma_f32_16x16x32_bf16 v[82:85], v[226:229], v[200:203], v[82:85]
	v_mfma_f32_16x16x32_bf16 v[74:77], v[226:229], v[204:207], v[74:77]
	v_mfma_f32_16x16x32_bf16 v[66:69], v[226:229], v[208:211], v[66:69]
	s_waitcnt lgkmcnt(0)
	v_mfma_f32_16x16x32_bf16 v[58:61], v[130:133], v[134:137], v[58:61]
	ds_read_b128 v[226:229], v212 offset:14336
	v_mfma_f32_16x16x32_bf16 v[50:53], v[130:133], v[184:187], v[50:53]
	v_mfma_f32_16x16x32_bf16 v[42:45], v[130:133], v[188:191], v[42:45]
	v_mfma_f32_16x16x32_bf16 v[30:33], v[130:133], v[192:195], v[30:33]
	v_mfma_f32_16x16x32_bf16 v[14:17], v[130:133], v[196:199], v[14:17]
	v_mfma_f32_16x16x32_bf16 v[10:13], v[130:133], v[200:203], v[10:13]
	v_mfma_f32_16x16x32_bf16 v[6:9], v[130:133], v[204:207], v[6:9]
	v_mfma_f32_16x16x32_bf16 v[2:5], v[130:133], v[208:211], v[2:5]
	s_waitcnt vmcnt(0) lgkmcnt(0)
	s_barrier
	s_add_u32 s14, s14, 0x80
	s_addc_u32 s15, s15, 0
	s_add_i32 s20, s20, 0x10000
	s_add_i32 s19, s19, 1
	s_cmpk_eq_i32 s14, 0x800
	s_cbranch_scc1 .Lmyg1245_tail
	s_add_i32 s100, s20, 0xffff0000
	s_and_b32 s100, s100, 0x10000
	v_add_u32_e32 v0, s100, v179
	v_add3_u32 v212, v0, v180, v181
	v_add3_u32 v0, v0, v182, v181
	s_cmp_gt_u32 s19, 14
	s_cbranch_scc1 .Lmyg1245_nodma
	s_bitcmp1_b32 s101, 1
	s_cbranch_scc1 .Lmyg1245_defer
	s_setprio 3
	s_and_b32 s21, s20, 0x10000
	s_add_i32 s21, s21, 0
	s_add_i32 s22, s21, 0x2000
	s_add_i32 s21, s21, 0xa000
	v_add_u32_e32 v224, s21, v140
	v_lshl_add_u64 v[222:223], v[166:167], 0, s[14:15]
	v_readfirstlane_b32 s23, v224
	v_add_u32_e32 v224, s22, v140
	s_mov_b32 m0, s23
	v_readfirstlane_b32 s23, v224
	v_add_u32_e32 v224, s21, v142
	global_load_lds_dwordx4 v[222:223], off
	v_lshl_add_u64 v[222:223], v[156:157], 0, s[14:15]
	s_mov_b32 m0, s23
	v_readfirstlane_b32 s23, v224
	v_add_u32_e32 v224, s22, v142
	global_load_lds_dwordx4 v[222:223], off
	v_lshl_add_u64 v[222:223], v[164:165], 0, s[14:15]
	s_mov_b32 m0, s23
	v_readfirstlane_b32 s23, v224
	v_add_u32_e32 v224, s21, v144
	global_load_lds_dwordx4 v[222:223], off
	v_lshl_add_u64 v[222:223], v[154:155], 0, s[14:15]
	s_mov_b32 m0, s23
	v_readfirstlane_b32 s23, v224
	v_add_u32_e32 v224, s22, v144
	global_load_lds_dwordx4 v[222:223], off
	v_lshl_add_u64 v[222:223], v[160:161], 0, s[14:15]
	s_mov_b32 m0, s23
	v_readfirstlane_b32 s23, v224
	v_add_u32_e32 v224, s21, v146
	global_load_lds_dwordx4 v[222:223], off
	v_lshl_add_u64 v[222:223], v[152:153], 0, s[14:15]
	s_mov_b32 m0, s23
	v_readfirstlane_b32 s21, v224
	v_add_u32_e32 v224, s22, v146
	global_load_lds_dwordx4 v[222:223], off
	v_lshl_add_u64 v[222:223], v[158:159], 0, s[14:15]
	s_mov_b32 m0, s21
	v_readfirstlane_b32 s21, v224
	global_load_lds_dwordx4 v[222:223], off
	v_lshl_add_u64 v[222:223], v[150:151], 0, s[14:15]
	s_mov_b32 m0, s21
	s_nop 0
	global_load_lds_dwordx4 v[222:223], off
	s_setprio 0
	s_branch .Lmyg1245_nodma

;   DI unsigned rowoff(int m) const { int combo = m >> 9, n = m & 511, b = combo >> 1, g = combo & 1; return (unsigned)((b * SEQ + 16 * n) * EIN + col0 + g * 64); }
;   DI unsigned koff(int k) const { return (unsigned)((k >> 6) * EIN + (k & 63)); }
; DI void dma16(const void* g, unsigned char* l) { __builtin_amdgcn_global_load_lds((const unsigned*)g, (lds_u32_t*)(unsigned)(size_t)l, 16, 0, 0); }
; template <class AF, class EF>
; DI void gemm_run(unsigned char* lds, int wv, const AF& af, const bf16_t* __restrict__ Bt, int ldb, int M, int N, int K, const EF& ef, int blk_off) {
;     ...
;   for (int tile_ = first; tile_ < ntl_eff; tile_ += tstep) {
;     int nt, mt;
;     if (xmap) { nt = tile_ % ntiles; mt = (tile_ / ntiles) * 8 + ((int)blockIdx.x & 7); }
;     else { nt = tile_ % ntiles; mt = tile_ / ntiles; }
;     const int m0 = mt << 8, n0 = nt << 8;
;     f32x4 acc[4][8];
; #pragma unroll
;     for (int i = 0; i < 4; ++i)
; #pragma unroll
;       for (int j = 0; j < 8; ++j) acc[i][j] = (f32x4){0.f, 0.f, 0.f, 0.f};
;     unsigned aoff[4], boff[4];
;     const bf16_t* Ab = af.base();
; #pragma unroll
;     for (int i = 0; i < 4; ++i) {
;       int row = crow + 64 * i;
;       aoff[i] = af.rowoff(m0 + row);
;       int n = n0 + row; n = n < N ? n : N - 1;
;       boff[i] = (unsigned)(n * ldb + cch);
;     }
;     __syncthreads();
; #pragma unroll
;     for (int i = 0; i < 4; ++i) {
;       dma16(Ab + aoff[i] + af.koff(cch), sBase + 32768 + (i * 512 + tid) * 16);
;       dma16(Bt + boff[i], sBase + (i * 512 + tid) * 16);
;     }
.LBB0_1266:
	s_ashr_i32 s10, s12, 31
	s_lshr_b32 s10, s10, 28
	s_add_i32 s14, s12, s10
	s_ashr_i32 s13, s14, 4
	s_lshl_b32 s10, s13, 3
	s_or_b32 s15, s10, s78
	v_readlane_b32 s10, v254, 34
	v_readlane_b32 s11, v254, 35
	s_and_b64 s[10:11], s[10:11], exec
	s_cselect_b32 s10, s15, s13
	s_lshl_b32 s13, s10, 8
	s_and_b32 s10, s14, 0xfffff0
	s_sub_i32 s10, s12, s10
	s_lshl_b32 s14, s10, 8
	v_add_u32_e32 v3, s14, v163
	v_min_i32_e32 v3, 0xfff, v3
	v_lshl_or_b32 v6, v3, 10, v139
	v_add_u32_e32 v3, s14, v164
	v_min_i32_e32 v3, 0xfff, v3
	v_add_u32_e32 v2, s14, v137
	v_lshl_or_b32 v10, v3, 10, v139
	v_add_u32_e32 v3, s14, v165
	v_add_lshl_u32 v0, s13, v137, 10
	v_min_i32_e32 v2, 0xfff, v2
	v_min_i32_e32 v3, 0xfff, v3
	v_lshl_or_b32 v2, v2, 10, v139
	v_lshl_or_b32 v14, v3, 10, v139
	v_lshlrev_b64 v[16:17], 1, v[0:1]
	v_readfirstlane_b32 s10, v166
	v_mov_b32_e32 v3, v1
	v_add_lshl_u32 v4, s13, v163, 10
	v_lshl_add_u64 v[18:19], v[134:135], 0, v[16:17]
	s_mov_b32 m0, s10
	v_lshlrev_b64 v[2:3], 1, v[2:3]
	v_readfirstlane_b32 s10, v167
	v_mov_b32_e32 v5, v1
	s_barrier
; DI void vm_wait0() { asm volatile("s_waitcnt vmcnt(0)" ::: "memory"); }
;   DI unsigned rowoff(int m) const { int combo = m >> 9, n = m & 511, b = combo >> 1, g = combo & 1; return (unsigned)((b * SEQ + 16 * n) * EIN + col0 + g * 64); }
;   DI unsigned koff(int k) const { return (unsigned)((k >> 6) * EIN + (k & 63)); }
; DI void dma16(const void* g, unsigned char* l) { __builtin_amdgcn_global_load_lds((const unsigned*)g, (lds_u32_t*)(unsigned)(size_t)l, 16, 0, 0); }
; template <class AF, class EF>
; DI void gemm_run(unsigned char* lds, int wv, const AF& af, const bf16_t* __restrict__ Bt, int ldb, int M, int N, int K, const EF& ef, int blk_off) {
;     ...
;     const int m0 = mt << 8, n0 = nt << 8;
;     f32x4 acc[4][8];
; #pragma unroll
;     for (int i = 0; i < 4; ++i)
; #pragma unroll
;       for (int j = 0; j < 8; ++j) acc[i][j] = (f32x4){0.f, 0.f, 0.f, 0.f};
;     unsigned aoff[4], boff[4];
;     const bf16_t* Ab = af.base();
; #pragma unroll
;     for (int i = 0; i < 4; ++i) {
;       int row = crow + 64 * i;
;       aoff[i] = af.rowoff(m0 + row);
;       int n = n0 + row; n = n < N ? n : N - 1;
;       boff[i] = (unsigned)(n * ldb + cch);
;     }
;     __syncthreads();
; #pragma unroll
;     for (int i = 0; i < 4; ++i) {
;       dma16(Ab + aoff[i] + af.koff(cch), sBase + 32768 + (i * 512 + tid) * 16);
;       dma16(Bt + boff[i], sBase + (i * 512 + tid) * 16);
;     }
;     vm_wait0();
;     __syncthreads();
; #pragma unroll 1
;     for (int kt = 0; kt < nk; ++kt) {
;       unsigned char* cur = sBase + (kt & 1) * GST;
;       if (kt + 1 < nk) {
;         unsigned char* nxt = sBase + ((kt + 1) & 1) * GST;
;         const int k0 = (kt + 1) << 6;
; #pragma unroll
;         for (int i = 0; i < 4; ++i) {
;           dma16(Ab + aoff[i] + af.koff(k0 + cch), nxt + 32768 + (i * 512 + tid) * 16);
;           dma16(Bt + boff[i] + (unsigned)k0, nxt + (i * 512 + tid) * 16);
;         }
	global_load_lds_dwordx4 v[18:19], off
	v_lshl_add_u64 v[18:19], s[4:5], 0, v[2:3]
	s_mov_b32 m0, s10
	v_lshlrev_b64 v[4:5], 1, v[4:5]
	v_readfirstlane_b32 s10, v168
	v_mov_b32_e32 v7, v1
	v_add_lshl_u32 v8, s13, v164, 10
	global_load_lds_dwordx4 v[18:19], off
	v_lshl_add_u64 v[18:19], v[134:135], 0, v[4:5]
	s_mov_b32 m0, s10
	v_lshlrev_b64 v[6:7], 1, v[6:7]
	v_readfirstlane_b32 s10, v169
	v_mov_b32_e32 v9, v1
	global_load_lds_dwordx4 v[18:19], off
	v_lshl_add_u64 v[18:19], s[4:5], 0, v[6:7]
	s_mov_b32 m0, s10
	v_lshlrev_b64 v[8:9], 1, v[8:9]
	v_readfirstlane_b32 s10, v170
	v_mov_b32_e32 v11, v1
	v_add_lshl_u32 v12, s13, v165, 10
	global_load_lds_dwordx4 v[18:19], off
	v_lshl_add_u64 v[18:19], v[134:135], 0, v[8:9]
	s_mov_b32 m0, s10
	v_lshlrev_b64 v[10:11], 1, v[10:11]
	v_readfirstlane_b32 s10, v171
	v_mov_b32_e32 v13, v1
	global_load_lds_dwordx4 v[18:19], off
	v_lshl_add_u64 v[18:19], s[4:5], 0, v[10:11]
	s_mov_b32 m0, s10
	v_lshlrev_b64 v[12:13], 1, v[12:13]
	v_readfirstlane_b32 s10, v172
	v_mov_b32_e32 v15, v1
	global_load_lds_dwordx4 v[18:19], off
	v_lshl_add_u64 v[18:19], v[134:135], 0, v[12:13]
	s_mov_b32 m0, s10
	v_lshlrev_b64 v[14:15], 1, v[14:15]
	v_readfirstlane_b32 s10, v173
	global_load_lds_dwordx4 v[18:19], off
	v_lshl_add_u64 v[18:19], s[4:5], 0, v[14:15]
	s_mov_b32 m0, s10
	v_lshl_add_u64 v[152:153], s[8:9], 0, v[2:3]
	global_load_lds_dwordx4 v[18:19], off
	v_mov_b32_e32 v2, 0
	v_lshl_add_u64 v[146:147], s[8:9], 0, v[14:15]
	v_lshl_add_u64 v[148:149], s[8:9], 0, v[10:11]
	v_lshl_add_u64 v[150:151], s[8:9], 0, v[6:7]
	v_lshl_add_u64 v[154:155], v[144:145], 0, v[12:13]
	v_lshl_add_u64 v[156:157], v[144:145], 0, v[8:9]
	v_lshl_add_u64 v[158:159], v[144:145], 0, v[4:5]
	v_lshl_add_u64 v[160:161], v[144:145], 0, v[16:17]
	s_mov_b64 s[10:11], 0
	s_mov_b32 s15, 0x10000
	v_mov_b32_e32 v3, v2
	v_mov_b32_e32 v4, v2
	v_mov_b32_e32 v5, v2
	v_mov_b32_e32 v6, v2
	v_mov_b32_e32 v7, v2
	v_mov_b32_e32 v8, v2
	v_mov_b32_e32 v9, v2
	v_mov_b32_e32 v10, v2
	v_mov_b32_e32 v11, v2
	v_mov_b32_e32 v12, v2
	v_mov_b32_e32 v13, v2
	v_mov_b32_e32 v14, v2
	v_mov_b32_e32 v15, v2
	v_mov_b32_e32 v16, v2
	v_mov_b32_e32 v17, v2
	v_mov_b32_e32 v26, v2
	v_mov_b32_e32 v27, v2
	v_mov_b32_e32 v28, v2
	v_mov_b32_e32 v29, v2
	v_mov_b32_e32 v38, v2
	v_mov_b32_e32 v39, v2
	v_mov_b32_e32 v40, v2
	v_mov_b32_e32 v41, v2
	v_mov_b32_e32 v46, v2
	v_mov_b32_e32 v47, v2
	v_mov_b32_e32 v48, v2
	v_mov_b32_e32 v49, v2
	v_mov_b32_e32 v54, v2
	v_mov_b32_e32 v55, v2
	v_mov_b32_e32 v56, v2
	v_mov_b32_e32 v57, v2
	v_mov_b32_e32 v62, v2
	v_mov_b32_e32 v63, v2
	v_mov_b32_e32 v64, v2
	v_mov_b32_e32 v65, v2
	v_mov_b32_e32 v74, v2
	v_mov_b32_e32 v75, v2
	v_mov_b32_e32 v76, v2
	v_mov_b32_e32 v77, v2
	v_mov_b32_e32 v82, v2
	v_mov_b32_e32 v83, v2
	v_mov_b32_e32 v84, v2
	v_mov_b32_e32 v85, v2
	v_mov_b32_e32 v90, v2
	v_mov_b32_e32 v91, v2
	v_mov_b32_e32 v92, v2
	v_mov_b32_e32 v93, v2
	v_mov_b32_e32 v98, v2
	v_mov_b32_e32 v99, v2
	v_mov_b32_e32 v100, v2
	v_mov_b32_e32 v101, v2
	v_mov_b32_e32 v106, v2
	v_mov_b32_e32 v107, v2
	v_mov_b32_e32 v108, v2
	v_mov_b32_e32 v109, v2
	v_mov_b32_e32 v114, v2
	v_mov_b32_e32 v115, v2
	v_mov_b32_e32 v116, v2
	v_mov_b32_e32 v117, v2
	v_mov_b32_e32 v122, v2
	v_mov_b32_e32 v123, v2
	v_mov_b32_e32 v124, v2
	v_mov_b32_e32 v125, v2
	v_mov_b32_e32 v70, v2
	v_mov_b32_e32 v71, v2
	v_mov_b32_e32 v72, v2
	v_mov_b32_e32 v73, v2
	v_mov_b32_e32 v78, v2
	v_mov_b32_e32 v79, v2
	v_mov_b32_e32 v80, v2
	v_mov_b32_e32 v81, v2
	v_mov_b32_e32 v86, v2
	v_mov_b32_e32 v87, v2
	v_mov_b32_e32 v88, v2
	v_mov_b32_e32 v89, v2
	v_mov_b32_e32 v94, v2
	v_mov_b32_e32 v95, v2
	v_mov_b32_e32 v96, v2
	v_mov_b32_e32 v97, v2
	v_mov_b32_e32 v102, v2
	v_mov_b32_e32 v103, v2
	v_mov_b32_e32 v104, v2
	v_mov_b32_e32 v105, v2
	v_mov_b32_e32 v110, v2
	v_mov_b32_e32 v111, v2
	v_mov_b32_e32 v112, v2
	v_mov_b32_e32 v113, v2
	v_mov_b32_e32 v118, v2
	v_mov_b32_e32 v119, v2
	v_mov_b32_e32 v120, v2
	v_mov_b32_e32 v121, v2
	v_mov_b32_e32 v126, v2
	v_mov_b32_e32 v127, v2
	v_mov_b32_e32 v128, v2
	v_mov_b32_e32 v129, v2
	v_mov_b32_e32 v66, v2
	v_mov_b32_e32 v67, v2
	v_mov_b32_e32 v68, v2
	v_mov_b32_e32 v69, v2
	v_mov_b32_e32 v58, v2
	v_mov_b32_e32 v59, v2
	v_mov_b32_e32 v60, v2
	v_mov_b32_e32 v61, v2
	v_mov_b32_e32 v50, v2
	v_mov_b32_e32 v51, v2
	v_mov_b32_e32 v52, v2
	v_mov_b32_e32 v53, v2
	v_mov_b32_e32 v42, v2
	v_mov_b32_e32 v43, v2
	v_mov_b32_e32 v44, v2
	v_mov_b32_e32 v45, v2
	v_mov_b32_e32 v30, v2
	v_mov_b32_e32 v31, v2
	v_mov_b32_e32 v32, v2
	v_mov_b32_e32 v33, v2
	v_mov_b32_e32 v22, v2
	v_mov_b32_e32 v23, v2
	v_mov_b32_e32 v24, v2
	v_mov_b32_e32 v25, v2
	v_mov_b32_e32 v18, v2
	v_mov_b32_e32 v19, v2
	v_mov_b32_e32 v20, v2
	v_mov_b32_e32 v21, v2
	v_mov_b32_e32 v34, v2
	v_mov_b32_e32 v35, v2
	v_mov_b32_e32 v36, v2
	v_mov_b32_e32 v37, v2
	v_readlane_b32 s101, v254, 0
	s_nop 3
	s_lshr_b32 s101, s101, 8
	s_lshl_b32 s101, s101, 1
	s_and_b32 s16, s15, 0x10000
	s_add_i32 s16, s16, 0
	s_add_i32 s17, s16, 0x2000
	s_add_i32 s16, s16, 0xa000
	v_add_u32_e32 v224, s16, v136
	v_lshl_add_u64 v[222:223], v[160:161], 0, s[10:11]
	v_readfirstlane_b32 s18, v224
	v_add_u32_e32 v224, s17, v136
	s_mov_b32 m0, s18
	v_readfirstlane_b32 s18, v224
	v_add_u32_e32 v224, s16, v138
	global_load_lds_dwordx4 v[222:223], off
	v_lshl_add_u64 v[222:223], v[152:153], 0, s[10:11]
	s_mov_b32 m0, s18
	v_readfirstlane_b32 s18, v224
	v_add_u32_e32 v224, s17, v138
	global_load_lds_dwordx4 v[222:223], off
	v_lshl_add_u64 v[222:223], v[158:159], 0, s[10:11]
	s_mov_b32 m0, s18
	v_readfirstlane_b32 s18, v224
	v_add_u32_e32 v224, s16, v140
	global_load_lds_dwordx4 v[222:223], off
	v_lshl_add_u64 v[222:223], v[150:151], 0, s[10:11]
	s_mov_b32 m0, s18
	v_readfirstlane_b32 s18, v224
	v_add_u32_e32 v224, s17, v140
	global_load_lds_dwordx4 v[222:223], off
	v_lshl_add_u64 v[222:223], v[156:157], 0, s[10:11]
	s_mov_b32 m0, s18
	v_readfirstlane_b32 s18, v224
	v_add_u32_e32 v224, s16, v142
	global_load_lds_dwordx4 v[222:223], off
	v_lshl_add_u64 v[222:223], v[148:149], 0, s[10:11]
	s_mov_b32 m0, s18
	v_readfirstlane_b32 s16, v224
	v_add_u32_e32 v224, s17, v142
	global_load_lds_dwordx4 v[222:223], off
	v_lshl_add_u64 v[222:223], v[154:155], 0, s[10:11]
	s_mov_b32 m0, s16
	v_readfirstlane_b32 s16, v224
	global_load_lds_dwordx4 v[222:223], off
	v_lshl_add_u64 v[222:223], v[146:147], 0, s[10:11]
	s_mov_b32 m0, s16
	s_nop 0
	global_load_lds_dwordx4 v[222:223], off
	s_waitcnt vmcnt(8) lgkmcnt(0)
	s_barrier
	s_branch .LBB0_1268

; #define MFMA16(a, b, c) __builtin_amdgcn_mfma_f32_16x16x32_bf16((a), (b), (c), 0, 0, 0)
;   DI unsigned koff(int k) const { return (unsigned)((k >> 6) * EIN + (k & 63)); }
; DI void dma16(const void* g, unsigned char* l) { __builtin_amdgcn_global_load_lds((const unsigned*)g, (lds_u32_t*)(unsigned)(size_t)l, 16, 0, 0); }
; template <class AF, class EF>
; DI void gemm_run(unsigned char* lds, int wv, const AF& af, const bf16_t* __restrict__ Bt, int ldb, int M, int N, int K, const EF& ef, int blk_off) {
;     ...
;     for (int kt = 0; kt < nk; ++kt) {
;       unsigned char* cur = sBase + (kt & 1) * GST;
;       if (kt + 1 < nk) {
;         unsigned char* nxt = sBase + ((kt + 1) & 1) * GST;
;         const int k0 = (kt + 1) << 6;
; #pragma unroll
;         for (int i = 0; i < 4; ++i) {
;           dma16(Ab + aoff[i] + af.koff(k0 + cch), nxt + 32768 + (i * 512 + tid) * 16);
;           dma16(Bt + boff[i] + (unsigned)k0, nxt + (i * 512 + tid) * 16);
;         }
;       }
; #pragma unroll
;       for (int ks = 0; ks < 2; ++ks) {
;         bf16x8 wf[4], xf[8];
; #pragma unroll
;         for (int i = 0; i < 4; ++i) wf[i] = *(const bf16x8*)(cur + (wn * 64 + i * 16 + l15) * 128 + (((ks * 4 + q4) ^ swz) * 16));
; #pragma unroll
;         for (int j = 0; j < 8; ++j) xf[j] = *(const bf16x8*)(cur + 32768 + (wm * 128 + j * 16 + l15) * 128 + (((ks * 4 + q4) ^ swz) * 16));
; #pragma unroll
;         for (int i = 0; i < 4; ++i)
; #pragma unroll
;           for (int j = 0; j < 8; ++j) acc[i][j] = MFMA16(wf[i], xf[j], acc[i][j]);
;       }
.Lmyg1267_loop:
	s_waitcnt lgkmcnt(7)
	v_mfma_f32_16x16x32_bf16 v[126:129], v[130:133], v[180:183], v[126:129]
	ds_read_b128 v[226:229], v179 offset:10240
	s_waitcnt lgkmcnt(7)
	v_mfma_f32_16x16x32_bf16 v[118:121], v[130:133], v[184:187], v[118:121]
	s_waitcnt lgkmcnt(6)
	v_mfma_f32_16x16x32_bf16 v[110:113], v[130:133], v[188:191], v[110:113]
	s_waitcnt lgkmcnt(5)
	v_mfma_f32_16x16x32_bf16 v[102:105], v[130:133], v[192:195], v[102:105]
	s_waitcnt lgkmcnt(4)
	v_mfma_f32_16x16x32_bf16 v[94:97], v[130:133], v[196:199], v[94:97]
	s_waitcnt lgkmcnt(3)
	v_mfma_f32_16x16x32_bf16 v[86:89], v[130:133], v[200:203], v[86:89]
	s_waitcnt lgkmcnt(2)
	v_mfma_f32_16x16x32_bf16 v[78:81], v[130:133], v[204:207], v[78:81]
	s_waitcnt lgkmcnt(1)
	v_mfma_f32_16x16x32_bf16 v[70:73], v[130:133], v[208:211], v[70:73]
	s_waitcnt lgkmcnt(0)
	v_mfma_f32_16x16x32_bf16 v[122:125], v[226:229], v[180:183], v[122:125]
	ds_read_b128 v[130:133], v179 offset:12288
	v_mfma_f32_16x16x32_bf16 v[114:117], v[226:229], v[184:187], v[114:117]
	v_mfma_f32_16x16x32_bf16 v[106:109], v[226:229], v[188:191], v[106:109]
	v_mfma_f32_16x16x32_bf16 v[98:101], v[226:229], v[192:195], v[98:101]
	v_mfma_f32_16x16x32_bf16 v[90:93], v[226:229], v[196:199], v[90:93]
	v_mfma_f32_16x16x32_bf16 v[82:85], v[226:229], v[200:203], v[82:85]
	v_mfma_f32_16x16x32_bf16 v[74:77], v[226:229], v[204:207], v[74:77]
	v_mfma_f32_16x16x32_bf16 v[62:65], v[226:229], v[208:211], v[62:65]
	s_bitcmp1_b32 s101, 0
	s_cbranch_scc0 .Lmyg1267_noB
	s_andn2_b32 s101, s101, 1
	s_setprio 3
	s_and_b32 s16, s15, 0x10000
	s_add_i32 s16, s16, 0
	s_add_i32 s17, s16, 0x2000
	s_add_i32 s16, s16, 0xa000
	v_add_u32_e32 v224, s16, v136
	v_lshl_add_u64 v[222:223], v[160:161], 0, s[10:11]
	v_readfirstlane_b32 s18, v224
	v_add_u32_e32 v224, s17, v136
	s_mov_b32 m0, s18
	v_readfirstlane_b32 s18, v224
	v_add_u32_e32 v224, s16, v138
	global_load_lds_dwordx4 v[222:223], off
	v_lshl_add_u64 v[222:223], v[152:153], 0, s[10:11]
	s_mov_b32 m0, s18
	v_readfirstlane_b32 s18, v224
	v_add_u32_e32 v224, s17, v138
	global_load_lds_dwordx4 v[222:223], off
	v_lshl_add_u64 v[222:223], v[158:159], 0, s[10:11]
	s_mov_b32 m0, s18
	v_readfirstlane_b32 s18, v224
	v_add_u32_e32 v224, s16, v140
	global_load_lds_dwordx4 v[222:223], off
	v_lshl_add_u64 v[222:223], v[150:151], 0, s[10:11]
	s_mov_b32 m0, s18
	v_readfirstlane_b32 s18, v224
	v_add_u32_e32 v224, s17, v140
	global_load_lds_dwordx4 v[222:223], off
	v_lshl_add_u64 v[222:223], v[156:157], 0, s[10:11]
	s_mov_b32 m0, s18
	v_readfirstlane_b32 s18, v224
	v_add_u32_e32 v224, s16, v142
	global_load_lds_dwordx4 v[222:223], off
	v_lshl_add_u64 v[222:223], v[148:149], 0, s[10:11]
	s_mov_b32 m0, s18
	v_readfirstlane_b32 s16, v224
	v_add_u32_e32 v224, s17, v142
	global_load_lds_dwordx4 v[222:223], off
	v_lshl_add_u64 v[222:223], v[154:155], 0, s[10:11]
	s_mov_b32 m0, s16
	v_readfirstlane_b32 s16, v224
	global_load_lds_dwordx4 v[222:223], off
	v_lshl_add_u64 v[222:223], v[146:147], 0, s[10:11]
	s_mov_b32 m0, s16
	s_nop 0
	global_load_lds_dwordx4 v[222:223], off
	s_setprio 0
; #define MFMA16(a, b, c) __builtin_amdgcn_mfma_f32_16x16x32_bf16((a), (b), (c), 0, 0, 0)
; DI void vm_wait0() { asm volatile("s_waitcnt vmcnt(0)" ::: "memory"); }
;   DI unsigned koff(int k) const { return (unsigned)((k >> 6) * EIN + (k & 63)); }
; DI void dma16(const void* g, unsigned char* l) { __builtin_amdgcn_global_load_lds((const unsigned*)g, (lds_u32_t*)(unsigned)(size_t)l, 16, 0, 0); }
; template <class AF, class EF>
; DI void gemm_run(unsigned char* lds, int wv, const AF& af, const bf16_t* __restrict__ Bt, int ldb, int M, int N, int K, const EF& ef, int blk_off) {
;     ...
;       if (kt + 1 < nk) {
;         unsigned char* nxt = sBase + ((kt + 1) & 1) * GST;
;         const int k0 = (kt + 1) << 6;
; #pragma unroll
;         for (int i = 0; i < 4; ++i) {
;           dma16(Ab + aoff[i] + af.koff(k0 + cch), nxt + 32768 + (i * 512 + tid) * 16);
;           dma16(Bt + boff[i] + (unsigned)k0, nxt + (i * 512 + tid) * 16);
;         }
;     ...
; #pragma unroll
;       for (int ks = 0; ks < 2; ++ks) {
;         bf16x8 wf[4], xf[8];
; #pragma unroll
;         for (int i = 0; i < 4; ++i) wf[i] = *(const bf16x8*)(cur + (wn * 64 + i * 16 + l15) * 128 + (((ks * 4 + q4) ^ swz) * 16));
; #pragma unroll
;         for (int j = 0; j < 8; ++j) xf[j] = *(const bf16x8*)(cur + 32768 + (wm * 128 + j * 16 + l15) * 128 + (((ks * 4 + q4) ^ swz) * 16));
; #pragma unroll
;         for (int i = 0; i < 4; ++i)
; #pragma unroll
;           for (int j = 0; j < 8; ++j) acc[i][j] = MFMA16(wf[i], xf[j], acc[i][j]);
;       }
;       vm_wait0();
;       __syncthreads();
;     }
.Lmyg1267_noB:
	s_waitcnt lgkmcnt(0)
	v_mfma_f32_16x16x32_bf16 v[54:57], v[130:133], v[180:183], v[54:57]
	ds_read_b128 v[226:229], v179 offset:14336
	v_mfma_f32_16x16x32_bf16 v[46:49], v[130:133], v[184:187], v[46:49]
	v_add_u32_e32 v0, s100, v178
	v_mfma_f32_16x16x32_bf16 v[38:41], v[130:133], v[188:191], v[38:41]
	v_add3_u32 v179, v0, v175, v176
	v_mfma_f32_16x16x32_bf16 v[26:29], v[130:133], v[192:195], v[26:29]
	v_add3_u32 v0, v0, v177, v176
	v_mfma_f32_16x16x32_bf16 v[14:17], v[130:133], v[196:199], v[14:17]
	v_mfma_f32_16x16x32_bf16 v[10:13], v[130:133], v[200:203], v[10:13]
	v_mfma_f32_16x16x32_bf16 v[6:9], v[130:133], v[204:207], v[6:9]
	v_mfma_f32_16x16x32_bf16 v[2:5], v[130:133], v[208:211], v[2:5]
	s_waitcnt lgkmcnt(0)
	v_mfma_f32_16x16x32_bf16 v[66:69], v[226:229], v[180:183], v[66:69]
	ds_read_b128 v[130:133], v179 offset:8192
	ds_read_b128 v[180:183], v0 offset:40960
	v_mfma_f32_16x16x32_bf16 v[58:61], v[226:229], v[184:187], v[58:61]
	ds_read_b128 v[184:187], v0 offset:43008
	v_mfma_f32_16x16x32_bf16 v[50:53], v[226:229], v[188:191], v[50:53]
	ds_read_b128 v[188:191], v0 offset:45056
	v_mfma_f32_16x16x32_bf16 v[42:45], v[226:229], v[192:195], v[42:45]
	ds_read_b128 v[192:195], v0 offset:47104
	v_mfma_f32_16x16x32_bf16 v[30:33], v[226:229], v[196:199], v[30:33]
	ds_read_b128 v[196:199], v0 offset:49152
	v_mfma_f32_16x16x32_bf16 v[22:25], v[226:229], v[200:203], v[22:25]
	ds_read_b128 v[200:203], v0 offset:51200
	v_mfma_f32_16x16x32_bf16 v[18:21], v[226:229], v[204:207], v[18:21]
	ds_read_b128 v[204:207], v0 offset:53248
	v_mfma_f32_16x16x32_bf16 v[34:37], v[226:229], v[208:211], v[34:37]
	ds_read_b128 v[208:211], v0 offset:55296
	s_waitcnt lgkmcnt(7)
	v_mfma_f32_16x16x32_bf16 v[126:129], v[130:133], v[180:183], v[126:129]
	ds_read_b128 v[226:229], v179 offset:10240
	s_waitcnt lgkmcnt(7)
	v_mfma_f32_16x16x32_bf16 v[118:121], v[130:133], v[184:187], v[118:121]
	s_waitcnt lgkmcnt(6)
	v_mfma_f32_16x16x32_bf16 v[110:113], v[130:133], v[188:191], v[110:113]
	s_waitcnt lgkmcnt(5)
	v_mfma_f32_16x16x32_bf16 v[102:105], v[130:133], v[192:195], v[102:105]
	s_waitcnt lgkmcnt(4)
	v_mfma_f32_16x16x32_bf16 v[94:97], v[130:133], v[196:199], v[94:97]
	s_waitcnt lgkmcnt(3)
	v_mfma_f32_16x16x32_bf16 v[86:89], v[130:133], v[200:203], v[86:89]
	s_waitcnt lgkmcnt(2)
	v_mfma_f32_16x16x32_bf16 v[78:81], v[130:133], v[204:207], v[78:81]
	s_waitcnt lgkmcnt(1)
	v_mfma_f32_16x16x32_bf16 v[70:73], v[130:133], v[208:211], v[70:73]
	s_waitcnt lgkmcnt(0)
	v_mfma_f32_16x16x32_bf16 v[122:125], v[226:229], v[180:183], v[122:125]
	ds_read_b128 v[130:133], v179 offset:12288
	v_mfma_f32_16x16x32_bf16 v[114:117], v[226:229], v[184:187], v[114:117]
	v_mfma_f32_16x16x32_bf16 v[106:109], v[226:229], v[188:191], v[106:109]
	v_mfma_f32_16x16x32_bf16 v[98:101], v[226:229], v[192:195], v[98:101]
	v_mfma_f32_16x16x32_bf16 v[90:93], v[226:229], v[196:199], v[90:93]
	v_mfma_f32_16x16x32_bf16 v[82:85], v[226:229], v[200:203], v[82:85]
	v_mfma_f32_16x16x32_bf16 v[74:77], v[226:229], v[204:207], v[74:77]
	v_mfma_f32_16x16x32_bf16 v[62:65], v[226:229], v[208:211], v[62:65]
	s_waitcnt lgkmcnt(0)
	v_mfma_f32_16x16x32_bf16 v[54:57], v[130:133], v[180:183], v[54:57]
	ds_read_b128 v[226:229], v179 offset:14336
	v_mfma_f32_16x16x32_bf16 v[46:49], v[130:133], v[184:187], v[46:49]
	v_mfma_f32_16x16x32_bf16 v[38:41], v[130:133], v[188:191], v[38:41]
	v_mfma_f32_16x16x32_bf16 v[26:29], v[130:133], v[192:195], v[26:29]
	v_mfma_f32_16x16x32_bf16 v[14:17], v[130:133], v[196:199], v[14:17]
	v_mfma_f32_16x16x32_bf16 v[10:13], v[130:133], v[200:203], v[10:13]
	v_mfma_f32_16x16x32_bf16 v[6:9], v[130:133], v[204:207], v[6:9]
	v_mfma_f32_16x16x32_bf16 v[2:5], v[130:133], v[208:211], v[2:5]
	s_waitcnt vmcnt(0) lgkmcnt(0)
	s_barrier
	s_add_u32 s10, s10, 0x80
	s_addc_u32 s11, s11, 0
	s_add_i32 s15, s15, 0x10000
	s_cmpk_eq_i32 s10, 0x800
	s_cbranch_scc1 .Lmyg1267_tail
	s_add_i32 s100, s15, 0xffff0000
	s_and_b32 s100, s100, 0x10000
	v_add_u32_e32 v0, s100, v174
	v_add3_u32 v179, v0, v175, v176
	v_add3_u32 v0, v0, v177, v176
	s_cmpk_eq_i32 s10, 0x780
	s_cbranch_scc1 .Lmyg1267_nodma
	s_bitcmp1_b32 s101, 1
	s_cbranch_scc1 .Lmyg1267_defer
	s_setprio 3
	s_and_b32 s16, s15, 0x10000
	s_add_i32 s16, s16, 0
	s_add_i32 s17, s16, 0x2000
	s_add_i32 s16, s16, 0xa000
	v_add_u32_e32 v224, s16, v136
	v_lshl_add_u64 v[222:223], v[160:161], 0, s[10:11]
	v_readfirstlane_b32 s18, v224
	v_add_u32_e32 v224, s17, v136
	s_mov_b32 m0, s18
	v_readfirstlane_b32 s18, v224
	v_add_u32_e32 v224, s16, v138
	global_load_lds_dwordx4 v[222:223], off
	v_lshl_add_u64 v[222:223], v[152:153], 0, s[10:11]
	s_mov_b32 m0, s18
	v_readfirstlane_b32 s18, v224
	v_add_u32_e32 v224, s17, v138
	global_load_lds_dwordx4 v[222:223], off
	v_lshl_add_u64 v[222:223], v[158:159], 0, s[10:11]
	s_mov_b32 m0, s18
	v_readfirstlane_b32 s18, v224
	v_add_u32_e32 v224, s16, v140
	global_load_lds_dwordx4 v[222:223], off
	v_lshl_add_u64 v[222:223], v[150:151], 0, s[10:11]
	s_mov_b32 m0, s18
	v_readfirstlane_b32 s18, v224
	v_add_u32_e32 v224, s17, v140
	global_load_lds_dwordx4 v[222:223], off
	v_lshl_add_u64 v[222:223], v[156:157], 0, s[10:11]
	s_mov_b32 m0, s18
	v_readfirstlane_b32 s18, v224
	v_add_u32_e32 v224, s16, v142
	global_load_lds_dwordx4 v[222:223], off
	v_lshl_add_u64 v[222:223], v[148:149], 0, s[10:11]
	s_mov_b32 m0, s18
	v_readfirstlane_b32 s16, v224
	v_add_u32_e32 v224, s17, v142
	global_load_lds_dwordx4 v[222:223], off
	v_lshl_add_u64 v[222:223], v[154:155], 0, s[10:11]
	s_mov_b32 m0, s16
	v_readfirstlane_b32 s16, v224
	global_load_lds_dwordx4 v[222:223], off
	v_lshl_add_u64 v[222:223], v[146:147], 0, s[10:11]
	s_mov_b32 m0, s16
	s_nop 0
	global_load_lds_dwordx4 v[222:223], off
	s_setprio 0
	s_branch .Lmyg1267_nodma

;   DI unsigned rowoff(int m) const { int combo = m >> 9, n = m & 511, b = combo >> 1, g = combo & 1; return (unsigned)((b * SEQ + 16 * n) * EIN + col0 + g * 64); }
; template <class AF, class EF>
; DI void gemm_run(unsigned char* lds, int wv, const AF& af, const bf16_t* __restrict__ Bt, int ldb, int M, int N, int K, const EF& ef, int blk_off) {
;     ...
;   for (int tile_ = first; tile_ < ntl_eff; tile_ += tstep) {
;     int nt, mt;
;     if (xmap) { nt = tile_ % ntiles; mt = (tile_ / ntiles) * 8 + ((int)blockIdx.x & 7); }
;     else { nt = tile_ % ntiles; mt = tile_ / ntiles; }
;     const int m0 = mt << 8, n0 = nt << 8;
;     f32x4 acc[4][8];
; #pragma unroll
;     for (int i = 0; i < 4; ++i)
; #pragma unroll
;       for (int j = 0; j < 8; ++j) acc[i][j] = (f32x4){0.f, 0.f, 0.f, 0.f};
;     unsigned aoff[4], boff[4];
;     const bf16_t* Ab = af.base();
; #pragma unroll
;     for (int i = 0; i < 4; ++i) {
;       int row = crow + 64 * i;
;       aoff[i] = af.rowoff(m0 + row);
;       int n = n0 + row; n = n < N ? n : N - 1;
;       boff[i] = (unsigned)(n * ldb + cch);
;     }
;     __syncthreads();
.LBB0_1278:
	s_ashr_i32 s16, s18, 31
	s_lshr_b32 s16, s16, 30
	s_add_i32 s20, s18, s16
	s_ashr_i32 s19, s20, 2
	s_lshl_b32 s16, s19, 3
	s_or_b32 s21, s16, s78
	v_readlane_b32 s16, v254, 34
	v_readlane_b32 s17, v254, 35
	s_and_b64 s[16:17], s[16:17], exec
	s_cselect_b32 s16, s21, s19
	s_lshl_b32 s19, s16, 8
	s_and_b32 s16, s20, 0xfffffc
	s_sub_i32 s16, s18, s16
	s_lshl_b32 s20, s16, 8
	v_add_u32_e32 v3, s20, v168
	v_min_i32_e32 v3, 0x3ff, v3
	v_lshl_or_b32 v6, v3, 12, v145
	v_add_u32_e32 v3, s20, v169
	v_min_i32_e32 v3, 0x3ff, v3
	v_add_u32_e32 v2, s20, v143
	v_lshl_or_b32 v10, v3, 12, v145
	v_add_u32_e32 v3, s20, v170
	v_add_lshl_u32 v0, s19, v143, 12
	v_min_i32_e32 v2, 0x3ff, v2
	v_min_i32_e32 v3, 0x3ff, v3
	v_lshl_or_b32 v2, v2, 12, v145
	v_lshl_or_b32 v14, v3, 12, v145
	v_lshlrev_b64 v[16:17], 1, v[0:1]
	v_readfirstlane_b32 s16, v171
	v_mov_b32_e32 v3, v1
	v_add_lshl_u32 v4, s19, v168, 12
	v_lshl_add_u64 v[18:19], v[138:139], 0, v[16:17]
	s_mov_b32 m0, s16
	v_lshlrev_b64 v[2:3], 1, v[2:3]
	v_readfirstlane_b32 s16, v172
	v_mov_b32_e32 v5, v1
	s_waitcnt lgkmcnt(0)
	s_barrier
; DI void vm_wait0() { asm volatile("s_waitcnt vmcnt(0)" ::: "memory"); }
;   DI unsigned rowoff(int m) const { int combo = m >> 9, n = m & 511, b = combo >> 1, g = combo & 1; return (unsigned)((b * SEQ + 16 * n) * EIN + col0 + g * 64); }
;   DI unsigned koff(int k) const { return (unsigned)((k >> 6) * EIN + (k & 63)); }
; DI void dma16(const void* g, unsigned char* l) { __builtin_amdgcn_global_load_lds((const unsigned*)g, (lds_u32_t*)(unsigned)(size_t)l, 16, 0, 0); }
; template <class AF, class EF>
; DI void gemm_run(unsigned char* lds, int wv, const AF& af, const bf16_t* __restrict__ Bt, int ldb, int M, int N, int K, const EF& ef, int blk_off) {
;     ...
;     const int m0 = mt << 8, n0 = nt << 8;
;     f32x4 acc[4][8];
; #pragma unroll
;     for (int i = 0; i < 4; ++i)
; #pragma unroll
;       for (int j = 0; j < 8; ++j) acc[i][j] = (f32x4){0.f, 0.f, 0.f, 0.f};
;     unsigned aoff[4], boff[4];
;     const bf16_t* Ab = af.base();
; #pragma unroll
;     for (int i = 0; i < 4; ++i) {
;       int row = crow + 64 * i;
;       aoff[i] = af.rowoff(m0 + row);
;       int n = n0 + row; n = n < N ? n : N - 1;
;       boff[i] = (unsigned)(n * ldb + cch);
;     }
;     __syncthreads();
; #pragma unroll
;     for (int i = 0; i < 4; ++i) {
;       dma16(Ab + aoff[i] + af.koff(cch), sBase + 32768 + (i * 512 + tid) * 16);
;       dma16(Bt + boff[i], sBase + (i * 512 + tid) * 16);
;     }
;     vm_wait0();
;     __syncthreads();
; #pragma unroll 1
;     for (int kt = 0; kt < nk; ++kt) {
;       unsigned char* cur = sBase + (kt & 1) * GST;
;       if (kt + 1 < nk) {
;         unsigned char* nxt = sBase + ((kt + 1) & 1) * GST;
;         const int k0 = (kt + 1) << 6;
; #pragma unroll
;         for (int i = 0; i < 4; ++i) {
;           dma16(Ab + aoff[i] + af.koff(k0 + cch), nxt + 32768 + (i * 512 + tid) * 16);
;           dma16(Bt + boff[i] + (unsigned)k0, nxt + (i * 512 + tid) * 16);
;         }
	global_load_lds_dwordx4 v[18:19], off
	v_lshl_add_u64 v[18:19], s[4:5], 0, v[2:3]
	s_mov_b32 m0, s16
	v_lshlrev_b64 v[4:5], 1, v[4:5]
	v_readfirstlane_b32 s16, v173
	v_mov_b32_e32 v7, v1
	v_add_lshl_u32 v8, s19, v169, 12
	global_load_lds_dwordx4 v[18:19], off
	v_lshl_add_u64 v[18:19], v[138:139], 0, v[4:5]
	s_mov_b32 m0, s16
	v_lshlrev_b64 v[6:7], 1, v[6:7]
	v_readfirstlane_b32 s16, v174
	v_mov_b32_e32 v9, v1
	global_load_lds_dwordx4 v[18:19], off
	v_lshl_add_u64 v[18:19], s[4:5], 0, v[6:7]
	s_mov_b32 m0, s16
	v_lshlrev_b64 v[8:9], 1, v[8:9]
	v_readfirstlane_b32 s16, v175
	v_mov_b32_e32 v11, v1
	v_add_lshl_u32 v12, s19, v170, 12
	global_load_lds_dwordx4 v[18:19], off
	v_lshl_add_u64 v[18:19], v[138:139], 0, v[8:9]
	s_mov_b32 m0, s16
	v_lshlrev_b64 v[10:11], 1, v[10:11]
	v_readfirstlane_b32 s16, v176
	v_mov_b32_e32 v13, v1
	global_load_lds_dwordx4 v[18:19], off
	v_lshl_add_u64 v[18:19], s[4:5], 0, v[10:11]
	s_mov_b32 m0, s16
	v_lshlrev_b64 v[12:13], 1, v[12:13]
	v_readfirstlane_b32 s16, v177
	v_mov_b32_e32 v15, v1
	global_load_lds_dwordx4 v[18:19], off
	v_lshl_add_u64 v[18:19], v[138:139], 0, v[12:13]
	s_mov_b32 m0, s16
	v_lshlrev_b64 v[14:15], 1, v[14:15]
	v_readfirstlane_b32 s16, v178
	global_load_lds_dwordx4 v[18:19], off
	v_lshl_add_u64 v[18:19], s[4:5], 0, v[14:15]
	s_mov_b32 m0, s16
	v_lshl_add_u64 v[156:157], s[14:15], 0, v[2:3]
	global_load_lds_dwordx4 v[18:19], off
	v_mov_b32_e32 v2, 0
	v_lshl_add_u64 v[150:151], s[14:15], 0, v[14:15]
	v_lshl_add_u64 v[152:153], s[14:15], 0, v[10:11]
	v_lshl_add_u64 v[154:155], s[14:15], 0, v[6:7]
	v_lshl_add_u64 v[158:159], v[148:149], 0, v[12:13]
	v_lshl_add_u64 v[160:161], v[148:149], 0, v[8:9]
	v_lshl_add_u64 v[164:165], v[148:149], 0, v[4:5]
	v_lshl_add_u64 v[166:167], v[148:149], 0, v[16:17]
	s_mov_b32 s21, 0
	s_mov_b64 s[16:17], 0
	s_mov_b32 s22, 0x10000
	v_mov_b32_e32 v3, v2
	v_mov_b32_e32 v4, v2
	v_mov_b32_e32 v5, v2
	v_mov_b32_e32 v6, v2
	v_mov_b32_e32 v7, v2
	v_mov_b32_e32 v8, v2
	v_mov_b32_e32 v9, v2
	v_mov_b32_e32 v10, v2
	v_mov_b32_e32 v11, v2
	v_mov_b32_e32 v12, v2
	v_mov_b32_e32 v13, v2
	v_mov_b32_e32 v14, v2
	v_mov_b32_e32 v15, v2
	v_mov_b32_e32 v16, v2
	v_mov_b32_e32 v17, v2
	v_mov_b32_e32 v30, v2
	v_mov_b32_e32 v31, v2
	v_mov_b32_e32 v32, v2
	v_mov_b32_e32 v33, v2
	v_mov_b32_e32 v42, v2
	v_mov_b32_e32 v43, v2
	v_mov_b32_e32 v44, v2
	v_mov_b32_e32 v45, v2
	v_mov_b32_e32 v50, v2
	v_mov_b32_e32 v51, v2
	v_mov_b32_e32 v52, v2
	v_mov_b32_e32 v53, v2
	v_mov_b32_e32 v58, v2
	v_mov_b32_e32 v59, v2
	v_mov_b32_e32 v60, v2
	v_mov_b32_e32 v61, v2
	v_mov_b32_e32 v66, v2
	v_mov_b32_e32 v67, v2
	v_mov_b32_e32 v68, v2
	v_mov_b32_e32 v69, v2
	v_mov_b32_e32 v74, v2
	v_mov_b32_e32 v75, v2
	v_mov_b32_e32 v76, v2
	v_mov_b32_e32 v77, v2
	v_mov_b32_e32 v82, v2
	v_mov_b32_e32 v83, v2
	v_mov_b32_e32 v84, v2
	v_mov_b32_e32 v85, v2
	v_mov_b32_e32 v90, v2
	v_mov_b32_e32 v91, v2
	v_mov_b32_e32 v92, v2
	v_mov_b32_e32 v93, v2
	v_mov_b32_e32 v98, v2
	v_mov_b32_e32 v99, v2
	v_mov_b32_e32 v100, v2
	v_mov_b32_e32 v101, v2
	v_mov_b32_e32 v106, v2
	v_mov_b32_e32 v107, v2
	v_mov_b32_e32 v108, v2
	v_mov_b32_e32 v109, v2
	v_mov_b32_e32 v114, v2
	v_mov_b32_e32 v115, v2
	v_mov_b32_e32 v116, v2
	v_mov_b32_e32 v117, v2
	v_mov_b32_e32 v122, v2
	v_mov_b32_e32 v123, v2
	v_mov_b32_e32 v124, v2
	v_mov_b32_e32 v125, v2
	v_mov_b32_e32 v70, v2
	v_mov_b32_e32 v71, v2
	v_mov_b32_e32 v72, v2
	v_mov_b32_e32 v73, v2
	v_mov_b32_e32 v78, v2
	v_mov_b32_e32 v79, v2
	v_mov_b32_e32 v80, v2
	v_mov_b32_e32 v81, v2
	v_mov_b32_e32 v86, v2
	v_mov_b32_e32 v87, v2
	v_mov_b32_e32 v88, v2
	v_mov_b32_e32 v89, v2
	v_mov_b32_e32 v94, v2
	v_mov_b32_e32 v95, v2
	v_mov_b32_e32 v96, v2
	v_mov_b32_e32 v97, v2
	v_mov_b32_e32 v102, v2
	v_mov_b32_e32 v103, v2
	v_mov_b32_e32 v104, v2
	v_mov_b32_e32 v105, v2
	v_mov_b32_e32 v110, v2
	v_mov_b32_e32 v111, v2
	v_mov_b32_e32 v112, v2
	v_mov_b32_e32 v113, v2
	v_mov_b32_e32 v118, v2
	v_mov_b32_e32 v119, v2
	v_mov_b32_e32 v120, v2
	v_mov_b32_e32 v121, v2
	v_mov_b32_e32 v126, v2
	v_mov_b32_e32 v127, v2
	v_mov_b32_e32 v128, v2
	v_mov_b32_e32 v129, v2
	v_mov_b32_e32 v62, v2
	v_mov_b32_e32 v63, v2
	v_mov_b32_e32 v64, v2
	v_mov_b32_e32 v65, v2
	v_mov_b32_e32 v54, v2
	v_mov_b32_e32 v55, v2
	v_mov_b32_e32 v56, v2
	v_mov_b32_e32 v57, v2
	v_mov_b32_e32 v46, v2
	v_mov_b32_e32 v47, v2
	v_mov_b32_e32 v48, v2
	v_mov_b32_e32 v49, v2
	v_mov_b32_e32 v38, v2
	v_mov_b32_e32 v39, v2
	v_mov_b32_e32 v40, v2
	v_mov_b32_e32 v41, v2
	v_mov_b32_e32 v26, v2
	v_mov_b32_e32 v27, v2
	v_mov_b32_e32 v28, v2
	v_mov_b32_e32 v29, v2
	v_mov_b32_e32 v22, v2
	v_mov_b32_e32 v23, v2
	v_mov_b32_e32 v24, v2
	v_mov_b32_e32 v25, v2
	v_mov_b32_e32 v34, v2
	v_mov_b32_e32 v35, v2
	v_mov_b32_e32 v36, v2
	v_mov_b32_e32 v37, v2
	v_mov_b32_e32 v18, v2
	v_mov_b32_e32 v19, v2
	v_mov_b32_e32 v20, v2
	v_mov_b32_e32 v21, v2
	v_readlane_b32 s101, v254, 0
	s_nop 3
	s_lshr_b32 s101, s101, 8
	s_lshl_b32 s101, s101, 1
	s_and_b32 s23, s22, 0x10000
	s_add_i32 s23, s23, 0
	s_add_i32 s24, s23, 0x2000
	s_add_i32 s23, s23, 0xa000
	v_add_u32_e32 v224, s23, v140
	v_lshl_add_u64 v[222:223], v[166:167], 0, s[16:17]
	v_readfirstlane_b32 s25, v224
	v_add_u32_e32 v224, s24, v140
	s_mov_b32 m0, s25
	v_readfirstlane_b32 s25, v224
	v_add_u32_e32 v224, s23, v142
	global_load_lds_dwordx4 v[222:223], off
	v_lshl_add_u64 v[222:223], v[156:157], 0, s[16:17]
	s_mov_b32 m0, s25
	v_readfirstlane_b32 s25, v224
	v_add_u32_e32 v224, s24, v142
	global_load_lds_dwordx4 v[222:223], off
	v_lshl_add_u64 v[222:223], v[164:165], 0, s[16:17]
	s_mov_b32 m0, s25
	v_readfirstlane_b32 s25, v224
	v_add_u32_e32 v224, s23, v144
	global_load_lds_dwordx4 v[222:223], off
	v_lshl_add_u64 v[222:223], v[154:155], 0, s[16:17]
	s_mov_b32 m0, s25
	v_readfirstlane_b32 s25, v224
	v_add_u32_e32 v224, s24, v144
	global_load_lds_dwordx4 v[222:223], off
	v_lshl_add_u64 v[222:223], v[160:161], 0, s[16:17]
	s_mov_b32 m0, s25
	v_readfirstlane_b32 s25, v224
	v_add_u32_e32 v224, s23, v146
	global_load_lds_dwordx4 v[222:223], off
	v_lshl_add_u64 v[222:223], v[152:153], 0, s[16:17]
	s_mov_b32 m0, s25
	v_readfirstlane_b32 s23, v224
	v_add_u32_e32 v224, s24, v146
	global_load_lds_dwordx4 v[222:223], off
	v_lshl_add_u64 v[222:223], v[158:159], 0, s[16:17]
	s_mov_b32 m0, s23
	v_readfirstlane_b32 s23, v224
	global_load_lds_dwordx4 v[222:223], off
	v_lshl_add_u64 v[222:223], v[150:151], 0, s[16:17]
	s_mov_b32 m0, s23
	s_nop 0
	global_load_lds_dwordx4 v[222:223], off
	s_waitcnt vmcnt(8) lgkmcnt(0)
	s_barrier
	s_branch .LBB0_1280

; #define MFMA16(a, b, c) __builtin_amdgcn_mfma_f32_16x16x32_bf16((a), (b), (c), 0, 0, 0)
;   DI unsigned koff(int k) const { return (unsigned)((k >> 6) * EIN + (k & 63)); }
; DI void dma16(const void* g, unsigned char* l) { __builtin_amdgcn_global_load_lds((const unsigned*)g, (lds_u32_t*)(unsigned)(size_t)l, 16, 0, 0); }
; template <class AF, class EF>
; DI void gemm_run(unsigned char* lds, int wv, const AF& af, const bf16_t* __restrict__ Bt, int ldb, int M, int N, int K, const EF& ef, int blk_off) {
;     ...
;     for (int kt = 0; kt < nk; ++kt) {
;       unsigned char* cur = sBase + (kt & 1) * GST;
;       if (kt + 1 < nk) {
;         unsigned char* nxt = sBase + ((kt + 1) & 1) * GST;
;         const int k0 = (kt + 1) << 6;
; #pragma unroll
;         for (int i = 0; i < 4; ++i) {
;           dma16(Ab + aoff[i] + af.koff(k0 + cch), nxt + 32768 + (i * 512 + tid) * 16);
;           dma16(Bt + boff[i] + (unsigned)k0, nxt + (i * 512 + tid) * 16);
;         }
;       }
; #pragma unroll
;       for (int ks = 0; ks < 2; ++ks) {
;         bf16x8 wf[4], xf[8];
; #pragma unroll
;         for (int i = 0; i < 4; ++i) wf[i] = *(const bf16x8*)(cur + (wn * 64 + i * 16 + l15) * 128 + (((ks * 4 + q4) ^ swz) * 16));
; #pragma unroll
;         for (int j = 0; j < 8; ++j) xf[j] = *(const bf16x8*)(cur + 32768 + (wm * 128 + j * 16 + l15) * 128 + (((ks * 4 + q4) ^ swz) * 16));
; #pragma unroll
;         for (int i = 0; i < 4; ++i)
; #pragma unroll
;           for (int j = 0; j < 8; ++j) acc[i][j] = MFMA16(wf[i], xf[j], acc[i][j]);
;       }
.Lmyg1279_loop:
	s_waitcnt lgkmcnt(7)
	v_mfma_f32_16x16x32_bf16 v[118:121], v[130:133], v[184:187], v[118:121]
	ds_read_b128 v[226:229], v212 offset:10240
	s_waitcnt lgkmcnt(7)
	v_mfma_f32_16x16x32_bf16 v[126:129], v[130:133], v[134:137], v[126:129]
	s_waitcnt lgkmcnt(6)
	v_mfma_f32_16x16x32_bf16 v[110:113], v[130:133], v[188:191], v[110:113]
	s_waitcnt lgkmcnt(5)
	v_mfma_f32_16x16x32_bf16 v[102:105], v[130:133], v[192:195], v[102:105]
	s_waitcnt lgkmcnt(4)
	v_mfma_f32_16x16x32_bf16 v[94:97], v[130:133], v[196:199], v[94:97]
	s_waitcnt lgkmcnt(3)
	v_mfma_f32_16x16x32_bf16 v[86:89], v[130:133], v[200:203], v[86:89]
	s_waitcnt lgkmcnt(2)
	v_mfma_f32_16x16x32_bf16 v[78:81], v[130:133], v[204:207], v[78:81]
	s_waitcnt lgkmcnt(1)
	v_mfma_f32_16x16x32_bf16 v[70:73], v[130:133], v[208:211], v[70:73]
	s_waitcnt lgkmcnt(0)
	v_mfma_f32_16x16x32_bf16 v[122:125], v[226:229], v[134:137], v[122:125]
	ds_read_b128 v[130:133], v212 offset:12288
	v_mfma_f32_16x16x32_bf16 v[114:117], v[226:229], v[184:187], v[114:117]
	v_mfma_f32_16x16x32_bf16 v[106:109], v[226:229], v[188:191], v[106:109]
	v_mfma_f32_16x16x32_bf16 v[98:101], v[226:229], v[192:195], v[98:101]
	v_mfma_f32_16x16x32_bf16 v[90:93], v[226:229], v[196:199], v[90:93]
	v_mfma_f32_16x16x32_bf16 v[82:85], v[226:229], v[200:203], v[82:85]
	v_mfma_f32_16x16x32_bf16 v[74:77], v[226:229], v[204:207], v[74:77]
	v_mfma_f32_16x16x32_bf16 v[66:69], v[226:229], v[208:211], v[66:69]
	s_bitcmp1_b32 s101, 0
	s_cbranch_scc0 .Lmyg1279_noB
	s_andn2_b32 s101, s101, 1
	s_setprio 3
	s_and_b32 s23, s22, 0x10000
	s_add_i32 s23, s23, 0
	s_add_i32 s24, s23, 0x2000
	s_add_i32 s23, s23, 0xa000
	v_add_u32_e32 v224, s23, v140
	v_lshl_add_u64 v[222:223], v[166:167], 0, s[16:17]
	v_readfirstlane_b32 s25, v224
	v_add_u32_e32 v224, s24, v140
	s_mov_b32 m0, s25
	v_readfirstlane_b32 s25, v224
	v_add_u32_e32 v224, s23, v142
	global_load_lds_dwordx4 v[222:223], off
	v_lshl_add_u64 v[222:223], v[156:157], 0, s[16:17]
	s_mov_b32 m0, s25
	v_readfirstlane_b32 s25, v224
	v_add_u32_e32 v224, s24, v142
	global_load_lds_dwordx4 v[222:223], off
	v_lshl_add_u64 v[222:223], v[164:165], 0, s[16:17]
	s_mov_b32 m0, s25
	v_readfirstlane_b32 s25, v224
	v_add_u32_e32 v224, s23, v144
	global_load_lds_dwordx4 v[222:223], off
	v_lshl_add_u64 v[222:223], v[154:155], 0, s[16:17]
	s_mov_b32 m0, s25
	v_readfirstlane_b32 s25, v224
	v_add_u32_e32 v224, s24, v144
	global_load_lds_dwordx4 v[222:223], off
	v_lshl_add_u64 v[222:223], v[160:161], 0, s[16:17]
	s_mov_b32 m0, s25
	v_readfirstlane_b32 s25, v224
	v_add_u32_e32 v224, s23, v146
	global_load_lds_dwordx4 v[222:223], off
	v_lshl_add_u64 v[222:223], v[152:153], 0, s[16:17]
	s_mov_b32 m0, s25
	v_readfirstlane_b32 s23, v224
	v_add_u32_e32 v224, s24, v146
	global_load_lds_dwordx4 v[222:223], off
	v_lshl_add_u64 v[222:223], v[158:159], 0, s[16:17]
	s_mov_b32 m0, s23
	v_readfirstlane_b32 s23, v224
	global_load_lds_dwordx4 v[222:223], off
	v_lshl_add_u64 v[222:223], v[150:151], 0, s[16:17]
	s_mov_b32 m0, s23
	s_nop 0
	global_load_lds_dwordx4 v[222:223], off
	s_setprio 0
; #define MFMA16(a, b, c) __builtin_amdgcn_mfma_f32_16x16x32_bf16((a), (b), (c), 0, 0, 0)
; DI void vm_wait0() { asm volatile("s_waitcnt vmcnt(0)" ::: "memory"); }
;   DI unsigned koff(int k) const { return (unsigned)((k >> 6) * EIN + (k & 63)); }
; DI void dma16(const void* g, unsigned char* l) { __builtin_amdgcn_global_load_lds((const unsigned*)g, (lds_u32_t*)(unsigned)(size_t)l, 16, 0, 0); }
; template <class AF, class EF>
; DI void gemm_run(unsigned char* lds, int wv, const AF& af, const bf16_t* __restrict__ Bt, int ldb, int M, int N, int K, const EF& ef, int blk_off) {
;     ...
;       if (kt + 1 < nk) {
;         unsigned char* nxt = sBase + ((kt + 1) & 1) * GST;
;         const int k0 = (kt + 1) << 6;
; #pragma unroll
;         for (int i = 0; i < 4; ++i) {
;           dma16(Ab + aoff[i] + af.koff(k0 + cch), nxt + 32768 + (i * 512 + tid) * 16);
;           dma16(Bt + boff[i] + (unsigned)k0, nxt + (i * 512 + tid) * 16);
;         }
;     ...
; #pragma unroll
;       for (int ks = 0; ks < 2; ++ks) {
;         bf16x8 wf[4], xf[8];
; #pragma unroll
;         for (int i = 0; i < 4; ++i) wf[i] = *(const bf16x8*)(cur + (wn * 64 + i * 16 + l15) * 128 + (((ks * 4 + q4) ^ swz) * 16));
; #pragma unroll
;         for (int j = 0; j < 8; ++j) xf[j] = *(const bf16x8*)(cur + 32768 + (wm * 128 + j * 16 + l15) * 128 + (((ks * 4 + q4) ^ swz) * 16));
; #pragma unroll
;         for (int i = 0; i < 4; ++i)
; #pragma unroll
;           for (int j = 0; j < 8; ++j) acc[i][j] = MFMA16(wf[i], xf[j], acc[i][j]);
;       }
;       vm_wait0();
;       __syncthreads();
;     }
.Lmyg1279_noB:
	s_waitcnt lgkmcnt(0)
	v_mfma_f32_16x16x32_bf16 v[58:61], v[130:133], v[134:137], v[58:61]
	ds_read_b128 v[226:229], v212 offset:14336
	v_mfma_f32_16x16x32_bf16 v[50:53], v[130:133], v[184:187], v[50:53]
	v_add_u32_e32 v0, s100, v183
	v_mfma_f32_16x16x32_bf16 v[42:45], v[130:133], v[188:191], v[42:45]
	v_add3_u32 v212, v0, v180, v181
	v_mfma_f32_16x16x32_bf16 v[30:33], v[130:133], v[192:195], v[30:33]
	v_add3_u32 v0, v0, v182, v181
	v_mfma_f32_16x16x32_bf16 v[14:17], v[130:133], v[196:199], v[14:17]
	v_mfma_f32_16x16x32_bf16 v[10:13], v[130:133], v[200:203], v[10:13]
	v_mfma_f32_16x16x32_bf16 v[6:9], v[130:133], v[204:207], v[6:9]
	v_mfma_f32_16x16x32_bf16 v[2:5], v[130:133], v[208:211], v[2:5]
	s_waitcnt lgkmcnt(0)
	v_mfma_f32_16x16x32_bf16 v[54:57], v[226:229], v[184:187], v[54:57]
	ds_read_b128 v[130:133], v212 offset:8192
	ds_read_b128 v[184:187], v0 offset:43008
	v_mfma_f32_16x16x32_bf16 v[62:65], v[226:229], v[134:137], v[62:65]
	ds_read_b128 v[134:137], v0 offset:40960
	v_mfma_f32_16x16x32_bf16 v[46:49], v[226:229], v[188:191], v[46:49]
	ds_read_b128 v[188:191], v0 offset:45056
	v_mfma_f32_16x16x32_bf16 v[38:41], v[226:229], v[192:195], v[38:41]
	ds_read_b128 v[192:195], v0 offset:47104
	v_mfma_f32_16x16x32_bf16 v[26:29], v[226:229], v[196:199], v[26:29]
	ds_read_b128 v[196:199], v0 offset:49152
	v_mfma_f32_16x16x32_bf16 v[22:25], v[226:229], v[200:203], v[22:25]
	ds_read_b128 v[200:203], v0 offset:51200
	v_mfma_f32_16x16x32_bf16 v[34:37], v[226:229], v[204:207], v[34:37]
	ds_read_b128 v[204:207], v0 offset:53248
	v_mfma_f32_16x16x32_bf16 v[18:21], v[226:229], v[208:211], v[18:21]
	ds_read_b128 v[208:211], v0 offset:55296
	s_waitcnt lgkmcnt(7)
	v_mfma_f32_16x16x32_bf16 v[118:121], v[130:133], v[184:187], v[118:121]
	ds_read_b128 v[226:229], v212 offset:10240
	s_waitcnt lgkmcnt(7)
	v_mfma_f32_16x16x32_bf16 v[126:129], v[130:133], v[134:137], v[126:129]
	s_waitcnt lgkmcnt(6)
	v_mfma_f32_16x16x32_bf16 v[110:113], v[130:133], v[188:191], v[110:113]
	s_waitcnt lgkmcnt(5)
	v_mfma_f32_16x16x32_bf16 v[102:105], v[130:133], v[192:195], v[102:105]
	s_waitcnt lgkmcnt(4)
	v_mfma_f32_16x16x32_bf16 v[94:97], v[130:133], v[196:199], v[94:97]
	s_waitcnt lgkmcnt(3)
	v_mfma_f32_16x16x32_bf16 v[86:89], v[130:133], v[200:203], v[86:89]
	s_waitcnt lgkmcnt(2)
	v_mfma_f32_16x16x32_bf16 v[78:81], v[130:133], v[204:207], v[78:81]
	s_waitcnt lgkmcnt(1)
	v_mfma_f32_16x16x32_bf16 v[70:73], v[130:133], v[208:211], v[70:73]
	s_waitcnt lgkmcnt(0)
	v_mfma_f32_16x16x32_bf16 v[122:125], v[226:229], v[134:137], v[122:125]
	ds_read_b128 v[130:133], v212 offset:12288
	v_mfma_f32_16x16x32_bf16 v[114:117], v[226:229], v[184:187], v[114:117]
	v_mfma_f32_16x16x32_bf16 v[106:109], v[226:229], v[188:191], v[106:109]
	v_mfma_f32_16x16x32_bf16 v[98:101], v[226:229], v[192:195], v[98:101]
	v_mfma_f32_16x16x32_bf16 v[90:93], v[226:229], v[196:199], v[90:93]
	v_mfma_f32_16x16x32_bf16 v[82:85], v[226:229], v[200:203], v[82:85]
	v_mfma_f32_16x16x32_bf16 v[74:77], v[226:229], v[204:207], v[74:77]
	v_mfma_f32_16x16x32_bf16 v[66:69], v[226:229], v[208:211], v[66:69]
	s_waitcnt lgkmcnt(0)
	v_mfma_f32_16x16x32_bf16 v[58:61], v[130:133], v[134:137], v[58:61]
	ds_read_b128 v[226:229], v212 offset:14336
	v_mfma_f32_16x16x32_bf16 v[50:53], v[130:133], v[184:187], v[50:53]
	v_mfma_f32_16x16x32_bf16 v[42:45], v[130:133], v[188:191], v[42:45]
	v_mfma_f32_16x16x32_bf16 v[30:33], v[130:133], v[192:195], v[30:33]
	v_mfma_f32_16x16x32_bf16 v[14:17], v[130:133], v[196:199], v[14:17]
	v_mfma_f32_16x16x32_bf16 v[10:13], v[130:133], v[200:203], v[10:13]
	v_mfma_f32_16x16x32_bf16 v[6:9], v[130:133], v[204:207], v[6:9]
	v_mfma_f32_16x16x32_bf16 v[2:5], v[130:133], v[208:211], v[2:5]
	s_waitcnt vmcnt(0) lgkmcnt(0)
	s_barrier
	s_add_u32 s16, s16, 0x80
	s_addc_u32 s17, s17, 0
	s_add_i32 s22, s22, 0x10000
	s_add_i32 s21, s21, 1
	s_cmpk_eq_i32 s16, 0x2000
	s_cbranch_scc1 .Lmyg1279_tail
	s_add_i32 s100, s22, 0xffff0000
	s_and_b32 s100, s100, 0x10000
	v_add_u32_e32 v0, s100, v179
	v_add3_u32 v212, v0, v180, v181
	v_add3_u32 v0, v0, v182, v181
	s_cmp_gt_u32 s21, 62
	s_cbranch_scc1 .Lmyg1279_nodma
	s_bitcmp1_b32 s101, 1
	s_cbranch_scc1 .Lmyg1279_defer
	s_setprio 3
	s_and_b32 s23, s22, 0x10000
	s_add_i32 s23, s23, 0
	s_add_i32 s24, s23, 0x2000
	s_add_i32 s23, s23, 0xa000
	v_add_u32_e32 v224, s23, v140
	v_lshl_add_u64 v[222:223], v[166:167], 0, s[16:17]
	v_readfirstlane_b32 s25, v224
	v_add_u32_e32 v224, s24, v140
	s_mov_b32 m0, s25
	v_readfirstlane_b32 s25, v224
	v_add_u32_e32 v224, s23, v142
	global_load_lds_dwordx4 v[222:223], off
	v_lshl_add_u64 v[222:223], v[156:157], 0, s[16:17]
	s_mov_b32 m0, s25
	v_readfirstlane_b32 s25, v224
	v_add_u32_e32 v224, s24, v142
	global_load_lds_dwordx4 v[222:223], off
	v_lshl_add_u64 v[222:223], v[164:165], 0, s[16:17]
	s_mov_b32 m0, s25
	v_readfirstlane_b32 s25, v224
	v_add_u32_e32 v224, s23, v144
	global_load_lds_dwordx4 v[222:223], off
	v_lshl_add_u64 v[222:223], v[154:155], 0, s[16:17]
	s_mov_b32 m0, s25
	v_readfirstlane_b32 s25, v224
	v_add_u32_e32 v224, s24, v144
	global_load_lds_dwordx4 v[222:223], off
	v_lshl_add_u64 v[222:223], v[160:161], 0, s[16:17]
	s_mov_b32 m0, s25
	v_readfirstlane_b32 s25, v224
	v_add_u32_e32 v224, s23, v146
	global_load_lds_dwordx4 v[222:223], off
	v_lshl_add_u64 v[222:223], v[152:153], 0, s[16:17]
	s_mov_b32 m0, s25
	v_readfirstlane_b32 s23, v224
	v_add_u32_e32 v224, s24, v146
	global_load_lds_dwordx4 v[222:223], off
	v_lshl_add_u64 v[222:223], v[158:159], 0, s[16:17]
	s_mov_b32 m0, s23
	v_readfirstlane_b32 s23, v224
	global_load_lds_dwordx4 v[222:223], off
	v_lshl_add_u64 v[222:223], v[150:151], 0, s[16:17]
	s_mov_b32 m0, s23
	s_nop 0
	global_load_lds_dwordx4 v[222:223], off
	s_setprio 0
	s_branch .Lmyg1279_nodma
